# FFN-in x4: wave halves no longer re-aligned around the SwiGLU epilogue (leading half starts its epilogue during the trailing half's last MFMA block), offset undone once after the last unit
# baseline (speedup 1.0000x reference)
; __device__ __forceinline__ unsigned cvt_pk_bf16(float lo, float hi) { unsigned r; asm volatile("v_cvt_pk_bf16_f32 %0, %1, %2" : "=v"(r) : "v"(lo), "v"(hi)); return r; }
; #define PG8_BAR __builtin_amdgcn_s_barrier()
;     __device__ __forceinline__ void half(const f32x4 (&acc)[2][4][2], int pm, int ai, int pn, int wr, int wc, int fr, int fq) const {
;         const int row0 = pm * BM + wr * 64 + fr, col0 = pn * HALF + wc * 32 + 8 * fq;
;         {
; #pragma unroll
;             for (int m = 0; m < 4; ++m) {
;                 float a[8], e[8];
; #pragma unroll
;                 for (int q = 0; q < 8; ++q) a[q] = acc[0][m][q >> 2][q & 3];
; #pragma unroll
;                 for (int q = 0; q < 8; ++q) e[q] = __builtin_amdgcn_exp2f(-a[q]);
; #pragma unroll
;                 for (int q = 0; q < 8; ++q) e[q] += 1.f;
; #pragma unroll
;                 for (int q = 0; q < 8; ++q) e[q] = __builtin_amdgcn_rcpf(e[q]);
; #pragma unroll
;                 for (int q = 0; q < 8; ++q) a[q] = a[q] * acc[1][m][q >> 2][q & 3] * e[q];
;                 u32x4 w; w.x = cvt_pk_bf16(a[0], a[1]); w.y = cvt_pk_bf16(a[2], a[3]); w.z = cvt_pk_bf16(a[4], a[5]); w.w = cvt_pk_bf16(a[6], a[7]);
;                 const int row = row0 + ai * HALF + m * 16;
;                 bf16_t* dst = O + (((size_t)(row >> 8) * (ldc >> 6) + (col0 >> 6)) * 256 + (row & 255)) * 64 + (col0 & 63);
;                 if (wt) asm volatile("global_store_dwordx4 %0, %1, off sc1\n\ts_nop 1" :: "v"(dst), "v"(w) : "memory"); else *(u32x4*)dst = w; }
; template <class Epi, class Sched, bool ALIGN_EPI = false, bool SP2 = false>
; __device__ __forceinline__ void gemm_phase(PG8_LAS unsigned char* lds, const Gemm g, const Sched& S, const Epi& E) {
;     ...
;         if constexpr (ALIGN_EPI) { if (wr == 0) PG8_BAR; }
.Lmy_peel_0_exit:
.LBB0_303:
	v_exp_f32_e64 v159, -v120
	v_exp_f32_e64 v160, -v121
	v_exp_f32_e64 v155, -v124
	v_exp_f32_e64 v156, -v125
	v_exp_f32_e64 v157, -v126
	v_exp_f32_e64 v161, -v122
	v_exp_f32_e64 v158, -v127
	v_exp_f32_e64 v162, -v123
	s_lshl_b32 s4, s54, 8
	v_add_f32_e32 v159, 1.0, v159
	s_lshl_b32 s5, s52, 7
	s_add_i32 s12, s4, s11
	v_add_f32_e32 v160, 1.0, v160
	v_rcp_f32_e32 v159, v159
	s_or_b32 s5, s5, s33
	s_ashr_i32 s12, s12, 8
	v_add_f32_e32 v155, 1.0, v155
	v_add_f32_e32 v156, 1.0, v156
	v_add_f32_e32 v157, 1.0, v157
	v_add_f32_e32 v161, 1.0, v161
	v_rcp_f32_e32 v160, v160
	s_ashr_i32 s50, s5, 6
	v_add_f32_e32 v158, 1.0, v158
	v_add_f32_e32 v162, 1.0, v162
	v_rcp_f32_e32 v155, v155
	v_rcp_f32_e32 v156, v156
	v_rcp_f32_e32 v157, v157
	v_rcp_f32_e32 v161, v161
	s_mulk_i32 s12, 0x58
	s_ashr_i32 s51, s50, 31
	v_rcp_f32_e32 v158, v158
	v_rcp_f32_e32 v162, v162
	v_mul_f32_e32 v112, v112, v120
	s_ashr_i32 s5, s12, 31
	v_mul_f32_e32 v120, v112, v159
	v_mul_f32_e32 v112, v113, v121
	s_add_u32 s12, s12, s50
	v_mul_f32_e32 v116, v116, v124
	v_mul_f32_e32 v117, v117, v125
	v_mul_f32_e32 v118, v118, v126
	v_mul_f32_e32 v121, v112, v160
	v_mul_f32_e32 v112, v114, v122
	s_addc_u32 s13, s5, s51
	v_mul_f32_e32 v116, v116, v155
	v_mul_f32_e32 v117, v117, v156
	v_mul_f32_e32 v118, v118, v157
	v_mul_f32_e32 v119, v119, v127
	v_mul_f32_e32 v122, v112, v161
	v_mul_f32_e32 v112, v115, v123
	s_lshl_b64 s[12:13], s[12:13], 15
	v_mul_f32_e32 v119, v119, v158
	v_mul_f32_e32 v115, v112, v162
	v_cvt_pk_bf16_f32 v112, v116, v117
	v_cvt_pk_bf16_f32 v113, v118, v119
	v_lshl_add_u64 v[116:117], v[138:139], 0, s[12:13]
	v_exp_f32_e64 v118, -v104
	v_lshl_add_u64 v[116:117], v[116:117], 0, v[136:137]
	v_exp_f32_e64 v119, -v105
	v_cvt_pk_bf16_f32 v114, v120, v121
	v_cvt_pk_bf16_f32 v115, v122, v115
	global_store_dwordx4 v[116:117], v[112:115], off
	v_exp_f32_e64 v120, -v106
	v_exp_f32_e64 v121, -v107
	v_exp_f32_e64 v112, -v108
	v_exp_f32_e64 v113, -v109
	v_exp_f32_e64 v114, -v110
	v_exp_f32_e64 v115, -v111
	v_add_f32_e32 v118, 1.0, v118
	v_add_f32_e32 v119, 1.0, v119
	v_rcp_f32_e32 v118, v118
	v_add_f32_e32 v112, 1.0, v112
	v_add_f32_e32 v120, 1.0, v120
	v_rcp_f32_e32 v119, v119
	v_add_f32_e32 v113, 1.0, v113
	v_add_f32_e32 v121, 1.0, v121
	v_rcp_f32_e32 v112, v112
	v_rcp_f32_e32 v120, v120
	v_add_f32_e32 v114, 1.0, v114
	v_add_f32_e32 v115, 1.0, v115
	v_rcp_f32_e32 v113, v113
	v_rcp_f32_e32 v121, v121
	v_mul_f32_e32 v96, v96, v104
	v_rcp_f32_e32 v114, v114
	v_rcp_f32_e32 v115, v115
	v_mul_f32_e32 v104, v96, v118
	v_mul_f32_e32 v96, v97, v105
	v_mul_f32_e32 v100, v100, v108
	v_mul_f32_e32 v105, v96, v119
	v_mul_f32_e32 v96, v98, v106
	v_mul_f32_e32 v100, v100, v112
	v_mul_f32_e32 v101, v101, v109
	v_mul_f32_e32 v106, v96, v120
	v_mul_f32_e32 v96, v99, v107
	v_mul_f32_e32 v101, v101, v113
	v_mul_f32_e32 v102, v102, v110
	v_mul_f32_e32 v103, v103, v111
	v_mul_f32_e32 v99, v96, v121
	v_cvt_pk_bf16_f32 v96, v100, v101
	v_exp_f32_e64 v100, -v88
	v_mul_f32_e32 v102, v102, v114
	v_mul_f32_e32 v103, v103, v115
	v_cvt_pk_bf16_f32 v97, v102, v103
	v_cvt_pk_bf16_f32 v98, v104, v105
	v_exp_f32_e64 v101, -v89
	v_cvt_pk_bf16_f32 v99, v106, v99
	global_store_dwordx4 v[116:117], v[96:99], off offset:2048
	v_exp_f32_e64 v102, -v90
	v_exp_f32_e64 v103, -v91
	v_exp_f32_e64 v96, -v92
	v_exp_f32_e64 v98, -v94
	v_exp_f32_e64 v97, -v93
	v_exp_f32_e64 v99, -v95
	v_add_f32_e32 v100, 1.0, v100
	v_add_f32_e32 v101, 1.0, v101
	v_rcp_f32_e32 v100, v100
	v_add_f32_e32 v96, 1.0, v96
	v_add_f32_e32 v98, 1.0, v98
	v_add_f32_e32 v102, 1.0, v102
	v_rcp_f32_e32 v101, v101
	v_add_f32_e32 v97, 1.0, v97
	v_add_f32_e32 v99, 1.0, v99
	v_add_f32_e32 v103, 1.0, v103
	v_rcp_f32_e32 v96, v96
	v_rcp_f32_e32 v98, v98
	v_rcp_f32_e32 v102, v102
	v_rcp_f32_e32 v97, v97
	v_rcp_f32_e32 v99, v99
	v_rcp_f32_e32 v103, v103
	v_mul_f32_e32 v80, v80, v88
	v_mul_f32_e32 v88, v80, v100
	v_mul_f32_e32 v80, v81, v89
	v_mul_f32_e32 v84, v84, v92
	v_mul_f32_e32 v86, v86, v94
	v_mul_f32_e32 v89, v80, v101
	v_mul_f32_e32 v80, v82, v90
	v_mul_f32_e32 v84, v84, v96
	v_mul_f32_e32 v85, v85, v93
	v_mul_f32_e32 v86, v86, v98
	v_mul_f32_e32 v87, v87, v95
	v_mul_f32_e32 v90, v80, v102
	v_mul_f32_e32 v80, v83, v91
	v_mul_f32_e32 v85, v85, v97
	v_mul_f32_e32 v87, v87, v99
	v_mul_f32_e32 v83, v80, v103
	v_cvt_pk_bf16_f32 v80, v84, v85
	v_cvt_pk_bf16_f32 v81, v86, v87
	v_add_co_u32_e32 v84, vcc, s60, v116
	v_exp_f32_e64 v86, -v72
	s_nop 0
	v_addc_co_u32_e32 v85, vcc, 0, v117, vcc
	v_exp_f32_e64 v87, -v73
	v_cvt_pk_bf16_f32 v82, v88, v89
	v_cvt_pk_bf16_f32 v83, v90, v83
	global_store_dwordx4 v[84:85], v[80:83], off
	v_exp_f32_e64 v88, -v74
	v_exp_f32_e64 v89, -v75
	v_exp_f32_e64 v81, -v77
	v_exp_f32_e64 v80, -v76
	v_exp_f32_e64 v82, -v78
	v_exp_f32_e64 v83, -v79
	v_add_f32_e32 v86, 1.0, v86
	v_add_f32_e32 v87, 1.0, v87
	v_rcp_f32_e32 v86, v86
	v_add_f32_e32 v81, 1.0, v81
	v_add_f32_e32 v88, 1.0, v88
	v_rcp_f32_e32 v87, v87
	v_add_f32_e32 v80, 1.0, v80
	v_add_f32_e32 v82, 1.0, v82
	v_add_f32_e32 v89, 1.0, v89
	v_rcp_f32_e32 v81, v81
	v_rcp_f32_e32 v88, v88
	v_add_f32_e32 v83, 1.0, v83
	v_rcp_f32_e32 v80, v80
	v_rcp_f32_e32 v82, v82
	v_rcp_f32_e32 v89, v89
	v_mul_f32_e32 v64, v64, v72
	v_rcp_f32_e32 v83, v83
	v_mul_f32_e32 v72, v64, v86
	v_mul_f32_e32 v64, v65, v73
	v_mul_f32_e32 v69, v69, v77
	v_mul_f32_e32 v73, v64, v87
	v_mul_f32_e32 v64, v66, v74
	v_mul_f32_e32 v68, v68, v76
	v_mul_f32_e32 v69, v69, v81
	v_mul_f32_e32 v70, v70, v78
	v_mul_f32_e32 v74, v64, v88
	v_mul_f32_e32 v64, v67, v75
	v_mul_f32_e32 v68, v68, v80
	v_mul_f32_e32 v70, v70, v82
	v_mul_f32_e32 v71, v71, v79
	v_mul_f32_e32 v67, v64, v89
	v_cvt_pk_bf16_f32 v64, v68, v69
; __device__ __forceinline__ unsigned cvt_pk_bf16(float lo, float hi) { unsigned r; asm volatile("v_cvt_pk_bf16_f32 %0, %1, %2" : "=v"(r) : "v"(lo), "v"(hi)); return r; }
; #define PG8_WAIT_V(n) asm volatile("s_waitcnt vmcnt(" #n ")" ::: "memory")
; #define PG8_BAR __builtin_amdgcn_s_barrier()
;     __device__ __forceinline__ void half(const f32x4 (&acc)[2][4][2], int pm, int ai, int pn, int wr, int wc, int fr, int fq) const {
;     ...
;             for (int m = 0; m < 4; ++m) {
;                 float a[8], e[8];
; #pragma unroll
;                 for (int q = 0; q < 8; ++q) a[q] = acc[0][m][q >> 2][q & 3];
; #pragma unroll
;                 for (int q = 0; q < 8; ++q) e[q] = __builtin_amdgcn_exp2f(-a[q]);
; #pragma unroll
;                 for (int q = 0; q < 8; ++q) e[q] += 1.f;
; #pragma unroll
;                 for (int q = 0; q < 8; ++q) e[q] = __builtin_amdgcn_rcpf(e[q]);
; #pragma unroll
;                 for (int q = 0; q < 8; ++q) a[q] = a[q] * acc[1][m][q >> 2][q & 3] * e[q];
;                 u32x4 w; w.x = cvt_pk_bf16(a[0], a[1]); w.y = cvt_pk_bf16(a[2], a[3]); w.z = cvt_pk_bf16(a[4], a[5]); w.w = cvt_pk_bf16(a[6], a[7]);
;                 const int row = row0 + ai * HALF + m * 16;
;                 bf16_t* dst = O + (((size_t)(row >> 8) * (ldc >> 6) + (col0 >> 6)) * 256 + (row & 255)) * 64 + (col0 & 63);
;                 if (wt) asm volatile("global_store_dwordx4 %0, %1, off sc1\n\ts_nop 1" :: "v"(dst), "v"(w) : "memory"); else *(u32x4*)dst = w; }
; template <class Epi, class Sched, bool ALIGN_EPI = false, bool SP2 = false>
; __device__ __forceinline__ void gemm_phase(PG8_LAS unsigned char* lds, const Gemm g, const Sched& S, const Epi& E) {
;     ...
;         if constexpr (ALIGN_EPI) { if (wr == 1) PG8_BAR; }
;     }
;     PG8_WAIT_V(0);
;     if constexpr (!ALIGN_EPI) { if (wr == 0) PG8_BAR; }
;     PG8_BAR;
	v_exp_f32_e64 v69, -v56
	v_mul_f32_e32 v71, v71, v83
	v_cvt_pk_bf16_f32 v65, v70, v71
	v_exp_f32_e64 v70, -v57
	v_cvt_pk_bf16_f32 v66, v72, v73
	v_cvt_pk_bf16_f32 v67, v74, v67
	global_store_dwordx4 v[84:85], v[64:67], off offset:2048
	v_exp_f32_e64 v71, -v58
	v_exp_f32_e64 v72, -v59
	v_exp_f32_e64 v65, -v60
	v_exp_f32_e64 v66, -v61
	v_add_f32_e32 v69, 1.0, v69
	v_add_f32_e32 v70, 1.0, v70
	v_rcp_f32_e32 v69, v69
	v_exp_f32_e64 v67, -v62
	v_add_f32_e32 v65, 1.0, v65
	v_add_f32_e32 v71, 1.0, v71
	v_rcp_f32_e32 v70, v70
	v_exp_f32_e64 v68, -v63
	v_add_f32_e32 v66, 1.0, v66
	v_add_f32_e32 v72, 1.0, v72
	v_rcp_f32_e32 v65, v65
	v_rcp_f32_e32 v71, v71
	v_rcp_f32_e32 v66, v66
	v_rcp_f32_e32 v72, v72
	v_mul_f32_e32 v48, v48, v56
	v_mul_f32_e32 v56, v48, v69
	v_mul_f32_e32 v48, v49, v57
	v_add_u32_e32 v64, s4, v151
	v_add_f32_e32 v67, 1.0, v67
	v_mul_f32_e32 v52, v52, v60
	v_mul_f32_e32 v57, v48, v70
	v_mul_f32_e32 v48, v50, v58
	v_lshrrev_b32_e32 v64, 8, v64
	v_add_f32_e32 v68, 1.0, v68
	v_rcp_f32_e32 v67, v67
	v_mul_f32_e32 v52, v52, v65
	v_mul_f32_e32 v53, v53, v61
	v_mul_f32_e32 v58, v48, v71
	v_mul_f32_e32 v48, v51, v59
	v_rcp_f32_e32 v68, v68
	v_mul_f32_e32 v53, v53, v66
	v_mul_f32_e32 v51, v48, v72
	v_cvt_pk_bf16_f32 v48, v52, v53
	v_mul_i32_i24_e32 v52, 0x58, v64
	v_ashrrev_i32_e32 v53, 31, v52
	v_mul_f32_e32 v54, v54, v62
	v_lshl_add_u64 v[52:53], v[52:53], 0, s[50:51]
	v_mul_f32_e32 v54, v54, v67
	v_mul_f32_e32 v55, v55, v63
	v_lshlrev_b64 v[52:53], 15, v[52:53]
	v_mul_f32_e32 v55, v55, v68
	v_cvt_pk_bf16_f32 v49, v54, v55
	v_lshl_add_u64 v[52:53], v[140:141], 0, v[52:53]
	v_exp_f32_e64 v54, -v40
	v_lshl_add_u64 v[52:53], v[52:53], 0, v[136:137]
	v_exp_f32_e64 v55, -v41
	v_cvt_pk_bf16_f32 v50, v56, v57
	v_cvt_pk_bf16_f32 v51, v58, v51
	global_store_dwordx4 v[52:53], v[48:51], off
	v_exp_f32_e64 v56, -v42
	v_exp_f32_e64 v57, -v43
	v_exp_f32_e64 v48, -v44
	v_exp_f32_e64 v49, -v45
	v_exp_f32_e64 v50, -v46
	v_exp_f32_e64 v51, -v47
	v_add_f32_e32 v54, 1.0, v54
	v_add_f32_e32 v55, 1.0, v55
	v_rcp_f32_e32 v54, v54
	v_add_f32_e32 v48, 1.0, v48
	v_add_f32_e32 v56, 1.0, v56
	v_rcp_f32_e32 v55, v55
	v_add_f32_e32 v49, 1.0, v49
	v_add_f32_e32 v57, 1.0, v57
	v_rcp_f32_e32 v48, v48
	v_rcp_f32_e32 v56, v56
	v_add_f32_e32 v50, 1.0, v50
	v_add_f32_e32 v51, 1.0, v51
	v_rcp_f32_e32 v49, v49
	v_rcp_f32_e32 v57, v57
	v_mul_f32_e32 v32, v32, v40
	v_rcp_f32_e32 v50, v50
	v_rcp_f32_e32 v51, v51
	v_mul_f32_e32 v40, v32, v54
	v_mul_f32_e32 v32, v33, v41
	v_mul_f32_e32 v36, v36, v44
	v_mul_f32_e32 v41, v32, v55
	v_mul_f32_e32 v32, v34, v42
	v_mul_f32_e32 v36, v36, v48
	v_mul_f32_e32 v37, v37, v45
	v_mul_f32_e32 v42, v32, v56
	v_mul_f32_e32 v32, v35, v43
	v_mul_f32_e32 v37, v37, v49
	v_mul_f32_e32 v38, v38, v46
	v_mul_f32_e32 v39, v39, v47
	v_mul_f32_e32 v35, v32, v57
	v_cvt_pk_bf16_f32 v32, v36, v37
	v_exp_f32_e64 v36, -v24
	v_mul_f32_e32 v38, v38, v50
	v_mul_f32_e32 v39, v39, v51
	v_cvt_pk_bf16_f32 v33, v38, v39
	v_cvt_pk_bf16_f32 v34, v40, v41
	v_exp_f32_e64 v37, -v25
	v_cvt_pk_bf16_f32 v35, v42, v35
	global_store_dwordx4 v[52:53], v[32:35], off offset:2048
	v_exp_f32_e64 v38, -v26
	v_exp_f32_e64 v39, -v27
	v_exp_f32_e64 v34, -v30
	v_exp_f32_e64 v32, -v28
	v_exp_f32_e64 v33, -v29
	v_exp_f32_e64 v35, -v31
	v_add_f32_e32 v36, 1.0, v36
	v_add_f32_e32 v37, 1.0, v37
	v_rcp_f32_e32 v36, v36
	v_add_f32_e32 v34, 1.0, v34
	v_add_f32_e32 v38, 1.0, v38
	v_rcp_f32_e32 v37, v37
	v_add_f32_e32 v32, 1.0, v32
	v_add_f32_e32 v33, 1.0, v33
	v_add_f32_e32 v35, 1.0, v35
	v_add_f32_e32 v39, 1.0, v39
	v_rcp_f32_e32 v34, v34
	v_rcp_f32_e32 v38, v38
	v_rcp_f32_e32 v32, v32
	v_rcp_f32_e32 v33, v33
	v_rcp_f32_e32 v35, v35
	v_rcp_f32_e32 v39, v39
	v_mul_f32_e32 v16, v16, v24
	v_mul_f32_e32 v24, v16, v36
	v_mul_f32_e32 v16, v17, v25
	v_mul_f32_e32 v22, v22, v30
	v_mul_f32_e32 v25, v16, v37
	v_mul_f32_e32 v16, v18, v26
	v_mul_f32_e32 v20, v20, v28
	v_mul_f32_e32 v21, v21, v29
	v_mul_f32_e32 v22, v22, v34
	v_mul_f32_e32 v23, v23, v31
	v_mul_f32_e32 v26, v16, v38
	v_mul_f32_e32 v16, v19, v27
	v_mul_f32_e32 v20, v20, v32
	v_mul_f32_e32 v21, v21, v33
	v_mul_f32_e32 v23, v23, v35
	v_mul_f32_e32 v19, v16, v39
	v_cvt_pk_bf16_f32 v16, v20, v21
	v_cvt_pk_bf16_f32 v17, v22, v23
	v_exp_f32_e64 v22, -v8
	v_exp_f32_e64 v23, -v9
	v_cvt_pk_bf16_f32 v18, v24, v25
	v_add_co_u32_e32 v20, vcc, s60, v52
	v_exp_f32_e64 v24, -v10
	v_cvt_pk_bf16_f32 v19, v26, v19
	s_nop 0
	v_addc_co_u32_e32 v21, vcc, 0, v53, vcc
	v_exp_f32_e64 v25, -v11
	global_store_dwordx4 v[20:21], v[16:19], off
	v_add_f32_e32 v22, 1.0, v22
	v_add_f32_e32 v23, 1.0, v23
	v_exp_f32_e64 v16, -v12
	v_exp_f32_e64 v17, -v13
	v_exp_f32_e64 v18, -v14
	v_exp_f32_e64 v19, -v15
	v_rcp_f32_e32 v22, v22
	v_add_f32_e32 v24, 1.0, v24
	v_rcp_f32_e32 v23, v23
	v_add_f32_e32 v25, 1.0, v25
	v_rcp_f32_e32 v24, v24
	v_add_f32_e32 v16, 1.0, v16
	v_add_f32_e32 v17, 1.0, v17
	v_add_f32_e32 v18, 1.0, v18
	v_add_f32_e32 v19, 1.0, v19
	v_rcp_f32_e32 v25, v25
	v_mul_f32_e32 v0, v0, v8
	v_rcp_f32_e32 v16, v16
	v_rcp_f32_e32 v17, v17
	v_rcp_f32_e32 v18, v18
	v_rcp_f32_e32 v19, v19
	v_mul_f32_e32 v8, v0, v22
	v_mul_f32_e32 v0, v1, v9
	v_mul_f32_e32 v9, v0, v23
	v_mul_f32_e32 v0, v2, v10
	v_mul_f32_e32 v10, v0, v24
	v_mul_f32_e32 v0, v3, v11
	v_mul_f32_e32 v4, v4, v12
	v_mul_f32_e32 v5, v5, v13
	v_mul_f32_e32 v6, v6, v14
	v_mul_f32_e32 v7, v7, v15
	v_mul_f32_e32 v3, v0, v25
	s_andn2_b64 vcc, exec, s[34:35]
	s_mov_b64 s[4:5], -1
	v_mul_f32_e32 v4, v4, v16
	v_mul_f32_e32 v5, v5, v17
	v_mul_f32_e32 v6, v6, v18
	v_mul_f32_e32 v7, v7, v19
	v_cvt_pk_bf16_f32 v0, v4, v5
	v_cvt_pk_bf16_f32 v1, v6, v7
	v_cvt_pk_bf16_f32 v2, v8, v9
	v_cvt_pk_bf16_f32 v3, v10, v3
	global_store_dwordx4 v[20:21], v[0:3], off offset:2048
	s_cbranch_vccnz .LBB0_292
	s_branch .LBB0_291
.LBB0_306:
	s_waitcnt vmcnt(0)
	s_and_b64 vcc, exec, s[38:39]
	s_cbranch_vccz .Lmy_na_0
	s_barrier
.Lmy_na_0:
	v_readlane_b32 s96, v254, 58
	v_readlane_b32 s92, v254, 60
	v_readlane_b32 s14, v254, 62
	v_readlane_b32 s97, v254, 59
	v_readlane_b32 s93, v254, 61
	v_readlane_b32 s15, v254, 63
	s_barrier

; __device__ __forceinline__ unsigned cvt_pk_bf16(float lo, float hi) { unsigned r; asm volatile("v_cvt_pk_bf16_f32 %0, %1, %2" : "=v"(r) : "v"(lo), "v"(hi)); return r; }
; #define PG8_BAR __builtin_amdgcn_s_barrier()
;     __device__ __forceinline__ void half(const f32x4 (&acc)[2][4][2], int pm, int ai, int pn, int wr, int wc, int fr, int fq) const {
;         const int row0 = pm * BM + wr * 64 + fr, col0 = pn * HALF + wc * 32 + 8 * fq;
;         {
; #pragma unroll
;             for (int m = 0; m < 4; ++m) {
;                 float a[8], e[8];
; #pragma unroll
;                 for (int q = 0; q < 8; ++q) a[q] = acc[0][m][q >> 2][q & 3];
; #pragma unroll
;                 for (int q = 0; q < 8; ++q) e[q] = __builtin_amdgcn_exp2f(-a[q]);
; #pragma unroll
;                 for (int q = 0; q < 8; ++q) e[q] += 1.f;
; #pragma unroll
;                 for (int q = 0; q < 8; ++q) e[q] = __builtin_amdgcn_rcpf(e[q]);
; #pragma unroll
;                 for (int q = 0; q < 8; ++q) a[q] = a[q] * acc[1][m][q >> 2][q & 3] * e[q];
;                 u32x4 w; w.x = cvt_pk_bf16(a[0], a[1]); w.y = cvt_pk_bf16(a[2], a[3]); w.z = cvt_pk_bf16(a[4], a[5]); w.w = cvt_pk_bf16(a[6], a[7]);
;                 const int row = row0 + ai * HALF + m * 16;
;                 bf16_t* dst = O + (((size_t)(row >> 8) * (ldc >> 6) + (col0 >> 6)) * 256 + (row & 255)) * 64 + (col0 & 63);
;                 if (wt) asm volatile("global_store_dwordx4 %0, %1, off sc1\n\ts_nop 1" :: "v"(dst), "v"(w) : "memory"); else *(u32x4*)dst = w; }
; template <class Epi, class Sched, bool ALIGN_EPI = false, bool SP2 = false>
; __device__ __forceinline__ void gemm_phase(PG8_LAS unsigned char* lds, const Gemm g, const Sched& S, const Epi& E) {
;     ...
;         if constexpr (ALIGN_EPI) { if (wr == 0) PG8_BAR; }
.Lmy_peel_5_exit:
.LBB0_1310:
	v_exp_f32_e64 v159, -v120
	v_exp_f32_e64 v160, -v121
	v_exp_f32_e64 v155, -v124
	v_exp_f32_e64 v156, -v125
	v_exp_f32_e64 v157, -v126
	v_exp_f32_e64 v161, -v122
	v_exp_f32_e64 v158, -v127
	v_exp_f32_e64 v162, -v123
	s_lshl_b32 s4, s60, 8
	v_add_f32_e32 v159, 1.0, v159
	s_lshl_b32 s5, s54, 7
	s_add_i32 s12, s4, s46
	v_add_f32_e32 v160, 1.0, v160
	v_rcp_f32_e32 v159, v159
	s_or_b32 s5, s5, s47
	s_ashr_i32 s12, s12, 8
	v_add_f32_e32 v155, 1.0, v155
	v_add_f32_e32 v156, 1.0, v156
	v_add_f32_e32 v157, 1.0, v157
	v_add_f32_e32 v161, 1.0, v161
	v_rcp_f32_e32 v160, v160
	s_ashr_i32 s50, s5, 6
	v_add_f32_e32 v158, 1.0, v158
	v_add_f32_e32 v162, 1.0, v162
	v_rcp_f32_e32 v155, v155
	v_rcp_f32_e32 v156, v156
	v_rcp_f32_e32 v157, v157
	v_rcp_f32_e32 v161, v161
	s_mulk_i32 s12, 0x58
	s_ashr_i32 s51, s50, 31
	v_rcp_f32_e32 v158, v158
	v_rcp_f32_e32 v162, v162
	v_mul_f32_e32 v112, v112, v120
	s_ashr_i32 s5, s12, 31
	v_mul_f32_e32 v120, v112, v159
	v_mul_f32_e32 v112, v113, v121
	s_add_u32 s12, s12, s50
	v_mul_f32_e32 v116, v116, v124
	v_mul_f32_e32 v117, v117, v125
	v_mul_f32_e32 v118, v118, v126
	v_mul_f32_e32 v121, v112, v160
	v_mul_f32_e32 v112, v114, v122
	s_addc_u32 s13, s5, s51
	v_mul_f32_e32 v116, v116, v155
	v_mul_f32_e32 v117, v117, v156
	v_mul_f32_e32 v118, v118, v157
	v_mul_f32_e32 v119, v119, v127
	v_mul_f32_e32 v122, v112, v161
	v_mul_f32_e32 v112, v115, v123
	s_lshl_b64 s[12:13], s[12:13], 15
	v_mul_f32_e32 v119, v119, v158
	v_mul_f32_e32 v115, v112, v162
	v_cvt_pk_bf16_f32 v112, v116, v117
	v_cvt_pk_bf16_f32 v113, v118, v119
	v_lshl_add_u64 v[116:117], v[138:139], 0, s[12:13]
	v_exp_f32_e64 v118, -v104
	v_lshl_add_u64 v[116:117], v[116:117], 0, v[136:137]
	v_exp_f32_e64 v119, -v105
	v_cvt_pk_bf16_f32 v114, v120, v121
	v_cvt_pk_bf16_f32 v115, v122, v115
	global_store_dwordx4 v[116:117], v[112:115], off
	v_exp_f32_e64 v120, -v106
	v_exp_f32_e64 v121, -v107
	v_exp_f32_e64 v112, -v108
	v_exp_f32_e64 v113, -v109
	v_exp_f32_e64 v114, -v110
	v_exp_f32_e64 v115, -v111
	v_add_f32_e32 v118, 1.0, v118
	v_add_f32_e32 v119, 1.0, v119
	v_rcp_f32_e32 v118, v118
	v_add_f32_e32 v112, 1.0, v112
	v_add_f32_e32 v120, 1.0, v120
	v_rcp_f32_e32 v119, v119
	v_add_f32_e32 v113, 1.0, v113
	v_add_f32_e32 v121, 1.0, v121
	v_rcp_f32_e32 v112, v112
	v_rcp_f32_e32 v120, v120
	v_add_f32_e32 v114, 1.0, v114
	v_add_f32_e32 v115, 1.0, v115
	v_rcp_f32_e32 v113, v113
	v_rcp_f32_e32 v121, v121
	v_mul_f32_e32 v96, v96, v104
	v_rcp_f32_e32 v114, v114
	v_rcp_f32_e32 v115, v115
	v_mul_f32_e32 v104, v96, v118
	v_mul_f32_e32 v96, v97, v105
	v_mul_f32_e32 v100, v100, v108
	v_mul_f32_e32 v105, v96, v119
	v_mul_f32_e32 v96, v98, v106
	v_mul_f32_e32 v100, v100, v112
	v_mul_f32_e32 v101, v101, v109
	v_mul_f32_e32 v106, v96, v120
	v_mul_f32_e32 v96, v99, v107
	v_mul_f32_e32 v101, v101, v113
	v_mul_f32_e32 v102, v102, v110
	v_mul_f32_e32 v103, v103, v111
	v_mul_f32_e32 v99, v96, v121
	v_cvt_pk_bf16_f32 v96, v100, v101
	v_exp_f32_e64 v100, -v88
	v_mul_f32_e32 v102, v102, v114
	v_mul_f32_e32 v103, v103, v115
	v_cvt_pk_bf16_f32 v97, v102, v103
	v_cvt_pk_bf16_f32 v98, v104, v105
	v_exp_f32_e64 v101, -v89
	v_cvt_pk_bf16_f32 v99, v106, v99
	global_store_dwordx4 v[116:117], v[96:99], off offset:2048
	v_exp_f32_e64 v102, -v90
	v_exp_f32_e64 v103, -v91
	v_exp_f32_e64 v96, -v92
	v_exp_f32_e64 v98, -v94
	v_exp_f32_e64 v97, -v93
	v_exp_f32_e64 v99, -v95
	v_add_f32_e32 v100, 1.0, v100
	v_add_f32_e32 v101, 1.0, v101
	v_rcp_f32_e32 v100, v100
	v_add_f32_e32 v96, 1.0, v96
	v_add_f32_e32 v98, 1.0, v98
	v_add_f32_e32 v102, 1.0, v102
	v_rcp_f32_e32 v101, v101
	v_add_f32_e32 v97, 1.0, v97
	v_add_f32_e32 v99, 1.0, v99
	v_add_f32_e32 v103, 1.0, v103
	v_rcp_f32_e32 v96, v96
	v_rcp_f32_e32 v98, v98
	v_rcp_f32_e32 v102, v102
	v_rcp_f32_e32 v97, v97
	v_rcp_f32_e32 v99, v99
	v_rcp_f32_e32 v103, v103
	v_mul_f32_e32 v80, v80, v88
	v_mul_f32_e32 v88, v80, v100
	v_mul_f32_e32 v80, v81, v89
	v_mul_f32_e32 v84, v84, v92
	v_mul_f32_e32 v86, v86, v94
	v_mul_f32_e32 v89, v80, v101
	v_mul_f32_e32 v80, v82, v90
	v_mul_f32_e32 v84, v84, v96
	v_mul_f32_e32 v85, v85, v93
	v_mul_f32_e32 v86, v86, v98
	v_mul_f32_e32 v87, v87, v95
	v_mul_f32_e32 v90, v80, v102
	v_mul_f32_e32 v80, v83, v91
	v_mul_f32_e32 v85, v85, v97
	v_mul_f32_e32 v87, v87, v99
	v_mul_f32_e32 v83, v80, v103
	v_cvt_pk_bf16_f32 v80, v84, v85
	v_cvt_pk_bf16_f32 v81, v86, v87
	v_add_co_u32_e32 v84, vcc, s62, v116
	v_exp_f32_e64 v86, -v72
	s_nop 0
	v_addc_co_u32_e32 v85, vcc, 0, v117, vcc
	v_exp_f32_e64 v87, -v73
	v_cvt_pk_bf16_f32 v82, v88, v89
	v_cvt_pk_bf16_f32 v83, v90, v83
	global_store_dwordx4 v[84:85], v[80:83], off
	v_exp_f32_e64 v88, -v74
	v_exp_f32_e64 v89, -v75
	v_exp_f32_e64 v81, -v77
	v_exp_f32_e64 v80, -v76
	v_exp_f32_e64 v82, -v78
	v_exp_f32_e64 v83, -v79
	v_add_f32_e32 v86, 1.0, v86
	v_add_f32_e32 v87, 1.0, v87
	v_rcp_f32_e32 v86, v86
	v_add_f32_e32 v81, 1.0, v81
	v_add_f32_e32 v88, 1.0, v88
	v_rcp_f32_e32 v87, v87
	v_add_f32_e32 v80, 1.0, v80
	v_add_f32_e32 v82, 1.0, v82
	v_add_f32_e32 v89, 1.0, v89
	v_rcp_f32_e32 v81, v81
	v_rcp_f32_e32 v88, v88
	v_add_f32_e32 v83, 1.0, v83
	v_rcp_f32_e32 v80, v80
	v_rcp_f32_e32 v82, v82
	v_rcp_f32_e32 v89, v89
	v_mul_f32_e32 v64, v64, v72
	v_rcp_f32_e32 v83, v83
	v_mul_f32_e32 v72, v64, v86
	v_mul_f32_e32 v64, v65, v73
	v_mul_f32_e32 v69, v69, v77
	v_mul_f32_e32 v73, v64, v87
	v_mul_f32_e32 v64, v66, v74
	v_mul_f32_e32 v68, v68, v76
	v_mul_f32_e32 v69, v69, v81
	v_mul_f32_e32 v70, v70, v78
	v_mul_f32_e32 v74, v64, v88
	v_mul_f32_e32 v64, v67, v75
	v_mul_f32_e32 v68, v68, v80
	v_mul_f32_e32 v70, v70, v82
	v_mul_f32_e32 v71, v71, v79
	v_mul_f32_e32 v67, v64, v89
	v_cvt_pk_bf16_f32 v64, v68, v69
; __device__ __forceinline__ unsigned cvt_pk_bf16(float lo, float hi) { unsigned r; asm volatile("v_cvt_pk_bf16_f32 %0, %1, %2" : "=v"(r) : "v"(lo), "v"(hi)); return r; }
; #define PG8_WAIT_V(n) asm volatile("s_waitcnt vmcnt(" #n ")" ::: "memory")
; #define PG8_BAR __builtin_amdgcn_s_barrier()
;     __device__ __forceinline__ void half(const f32x4 (&acc)[2][4][2], int pm, int ai, int pn, int wr, int wc, int fr, int fq) const {
;     ...
;             for (int m = 0; m < 4; ++m) {
;                 float a[8], e[8];
; #pragma unroll
;                 for (int q = 0; q < 8; ++q) a[q] = acc[0][m][q >> 2][q & 3];
; #pragma unroll
;                 for (int q = 0; q < 8; ++q) e[q] = __builtin_amdgcn_exp2f(-a[q]);
; #pragma unroll
;                 for (int q = 0; q < 8; ++q) e[q] += 1.f;
; #pragma unroll
;                 for (int q = 0; q < 8; ++q) e[q] = __builtin_amdgcn_rcpf(e[q]);
; #pragma unroll
;                 for (int q = 0; q < 8; ++q) a[q] = a[q] * acc[1][m][q >> 2][q & 3] * e[q];
;                 u32x4 w; w.x = cvt_pk_bf16(a[0], a[1]); w.y = cvt_pk_bf16(a[2], a[3]); w.z = cvt_pk_bf16(a[4], a[5]); w.w = cvt_pk_bf16(a[6], a[7]);
;                 const int row = row0 + ai * HALF + m * 16;
;                 bf16_t* dst = O + (((size_t)(row >> 8) * (ldc >> 6) + (col0 >> 6)) * 256 + (row & 255)) * 64 + (col0 & 63);
;                 if (wt) asm volatile("global_store_dwordx4 %0, %1, off sc1\n\ts_nop 1" :: "v"(dst), "v"(w) : "memory"); else *(u32x4*)dst = w; }
; template <class Epi, class Sched, bool ALIGN_EPI = false, bool SP2 = false>
; __device__ __forceinline__ void gemm_phase(PG8_LAS unsigned char* lds, const Gemm g, const Sched& S, const Epi& E) {
;     ...
;         if constexpr (ALIGN_EPI) { if (wr == 1) PG8_BAR; }
;     }
;     PG8_WAIT_V(0);
;     if constexpr (!ALIGN_EPI) { if (wr == 0) PG8_BAR; }
;     PG8_BAR;
	v_exp_f32_e64 v69, -v56
	v_mul_f32_e32 v71, v71, v83
	v_cvt_pk_bf16_f32 v65, v70, v71
	v_exp_f32_e64 v70, -v57
	v_cvt_pk_bf16_f32 v66, v72, v73
	v_cvt_pk_bf16_f32 v67, v74, v67
	global_store_dwordx4 v[84:85], v[64:67], off offset:2048
	v_exp_f32_e64 v71, -v58
	v_exp_f32_e64 v72, -v59
	v_exp_f32_e64 v65, -v60
	v_exp_f32_e64 v66, -v61
	v_add_f32_e32 v69, 1.0, v69
	v_add_f32_e32 v70, 1.0, v70
	v_rcp_f32_e32 v69, v69
	v_exp_f32_e64 v67, -v62
	v_add_f32_e32 v65, 1.0, v65
	v_add_f32_e32 v71, 1.0, v71
	v_rcp_f32_e32 v70, v70
	v_exp_f32_e64 v68, -v63
	v_add_f32_e32 v66, 1.0, v66
	v_add_f32_e32 v72, 1.0, v72
	v_rcp_f32_e32 v65, v65
	v_rcp_f32_e32 v71, v71
	v_rcp_f32_e32 v66, v66
	v_rcp_f32_e32 v72, v72
	v_mul_f32_e32 v48, v48, v56
	v_mul_f32_e32 v56, v48, v69
	v_mul_f32_e32 v48, v49, v57
	v_add_u32_e32 v64, s4, v151
	v_add_f32_e32 v67, 1.0, v67
	v_mul_f32_e32 v52, v52, v60
	v_mul_f32_e32 v57, v48, v70
	v_mul_f32_e32 v48, v50, v58
	v_lshrrev_b32_e32 v64, 8, v64
	v_add_f32_e32 v68, 1.0, v68
	v_rcp_f32_e32 v67, v67
	v_mul_f32_e32 v52, v52, v65
	v_mul_f32_e32 v53, v53, v61
	v_mul_f32_e32 v58, v48, v71
	v_mul_f32_e32 v48, v51, v59
	v_rcp_f32_e32 v68, v68
	v_mul_f32_e32 v53, v53, v66
	v_mul_f32_e32 v51, v48, v72
	v_cvt_pk_bf16_f32 v48, v52, v53
	v_mul_i32_i24_e32 v52, 0x58, v64
	v_ashrrev_i32_e32 v53, 31, v52
	v_mul_f32_e32 v54, v54, v62
	v_lshl_add_u64 v[52:53], v[52:53], 0, s[50:51]
	v_mul_f32_e32 v54, v54, v67
	v_mul_f32_e32 v55, v55, v63
	v_lshlrev_b64 v[52:53], 15, v[52:53]
	v_mul_f32_e32 v55, v55, v68
	v_cvt_pk_bf16_f32 v49, v54, v55
	v_lshl_add_u64 v[52:53], v[140:141], 0, v[52:53]
	v_exp_f32_e64 v54, -v40
	v_lshl_add_u64 v[52:53], v[52:53], 0, v[136:137]
	v_exp_f32_e64 v55, -v41
	v_cvt_pk_bf16_f32 v50, v56, v57
	v_cvt_pk_bf16_f32 v51, v58, v51
	global_store_dwordx4 v[52:53], v[48:51], off
	v_exp_f32_e64 v56, -v42
	v_exp_f32_e64 v57, -v43
	v_exp_f32_e64 v48, -v44
	v_exp_f32_e64 v49, -v45
	v_exp_f32_e64 v50, -v46
	v_exp_f32_e64 v51, -v47
	v_add_f32_e32 v54, 1.0, v54
	v_add_f32_e32 v55, 1.0, v55
	v_rcp_f32_e32 v54, v54
	v_add_f32_e32 v48, 1.0, v48
	v_add_f32_e32 v56, 1.0, v56
	v_rcp_f32_e32 v55, v55
	v_add_f32_e32 v49, 1.0, v49
	v_add_f32_e32 v57, 1.0, v57
	v_rcp_f32_e32 v48, v48
	v_rcp_f32_e32 v56, v56
	v_add_f32_e32 v50, 1.0, v50
	v_add_f32_e32 v51, 1.0, v51
	v_rcp_f32_e32 v49, v49
	v_rcp_f32_e32 v57, v57
	v_mul_f32_e32 v32, v32, v40
	v_rcp_f32_e32 v50, v50
	v_rcp_f32_e32 v51, v51
	v_mul_f32_e32 v40, v32, v54
	v_mul_f32_e32 v32, v33, v41
	v_mul_f32_e32 v36, v36, v44
	v_mul_f32_e32 v41, v32, v55
	v_mul_f32_e32 v32, v34, v42
	v_mul_f32_e32 v36, v36, v48
	v_mul_f32_e32 v37, v37, v45
	v_mul_f32_e32 v42, v32, v56
	v_mul_f32_e32 v32, v35, v43
	v_mul_f32_e32 v37, v37, v49
	v_mul_f32_e32 v38, v38, v46
	v_mul_f32_e32 v39, v39, v47
	v_mul_f32_e32 v35, v32, v57
	v_cvt_pk_bf16_f32 v32, v36, v37
	v_exp_f32_e64 v36, -v24
	v_mul_f32_e32 v38, v38, v50
	v_mul_f32_e32 v39, v39, v51
	v_cvt_pk_bf16_f32 v33, v38, v39
	v_cvt_pk_bf16_f32 v34, v40, v41
	v_exp_f32_e64 v37, -v25
	v_cvt_pk_bf16_f32 v35, v42, v35
	global_store_dwordx4 v[52:53], v[32:35], off offset:2048
	v_exp_f32_e64 v38, -v26
	v_exp_f32_e64 v39, -v27
	v_exp_f32_e64 v34, -v30
	v_exp_f32_e64 v32, -v28
	v_exp_f32_e64 v33, -v29
	v_exp_f32_e64 v35, -v31
	v_add_f32_e32 v36, 1.0, v36
	v_add_f32_e32 v37, 1.0, v37
	v_rcp_f32_e32 v36, v36
	v_add_f32_e32 v34, 1.0, v34
	v_add_f32_e32 v38, 1.0, v38
	v_rcp_f32_e32 v37, v37
	v_add_f32_e32 v32, 1.0, v32
	v_add_f32_e32 v33, 1.0, v33
	v_add_f32_e32 v35, 1.0, v35
	v_add_f32_e32 v39, 1.0, v39
	v_rcp_f32_e32 v34, v34
	v_rcp_f32_e32 v38, v38
	v_rcp_f32_e32 v32, v32
	v_rcp_f32_e32 v33, v33
	v_rcp_f32_e32 v35, v35
	v_rcp_f32_e32 v39, v39
	v_mul_f32_e32 v16, v16, v24
	v_mul_f32_e32 v24, v16, v36
	v_mul_f32_e32 v16, v17, v25
	v_mul_f32_e32 v22, v22, v30
	v_mul_f32_e32 v25, v16, v37
	v_mul_f32_e32 v16, v18, v26
	v_mul_f32_e32 v20, v20, v28
	v_mul_f32_e32 v21, v21, v29
	v_mul_f32_e32 v22, v22, v34
	v_mul_f32_e32 v23, v23, v31
	v_mul_f32_e32 v26, v16, v38
	v_mul_f32_e32 v16, v19, v27
	v_mul_f32_e32 v20, v20, v32
	v_mul_f32_e32 v21, v21, v33
	v_mul_f32_e32 v23, v23, v35
	v_mul_f32_e32 v19, v16, v39
	v_cvt_pk_bf16_f32 v16, v20, v21
	v_cvt_pk_bf16_f32 v17, v22, v23
	v_exp_f32_e64 v22, -v8
	v_exp_f32_e64 v23, -v9
	v_cvt_pk_bf16_f32 v18, v24, v25
	v_add_co_u32_e32 v20, vcc, s62, v52
	v_exp_f32_e64 v24, -v10
	v_cvt_pk_bf16_f32 v19, v26, v19
	s_nop 0
	v_addc_co_u32_e32 v21, vcc, 0, v53, vcc
	v_exp_f32_e64 v25, -v11
	global_store_dwordx4 v[20:21], v[16:19], off
	v_add_f32_e32 v22, 1.0, v22
	v_add_f32_e32 v23, 1.0, v23
	v_exp_f32_e64 v16, -v12
	v_exp_f32_e64 v17, -v13
	v_exp_f32_e64 v18, -v14
	v_exp_f32_e64 v19, -v15
	v_rcp_f32_e32 v22, v22
	v_add_f32_e32 v24, 1.0, v24
	v_rcp_f32_e32 v23, v23
	v_add_f32_e32 v25, 1.0, v25
	v_rcp_f32_e32 v24, v24
	v_add_f32_e32 v16, 1.0, v16
	v_add_f32_e32 v17, 1.0, v17
	v_add_f32_e32 v18, 1.0, v18
	v_add_f32_e32 v19, 1.0, v19
	v_rcp_f32_e32 v25, v25
	v_mul_f32_e32 v0, v0, v8
	v_rcp_f32_e32 v16, v16
	v_rcp_f32_e32 v17, v17
	v_rcp_f32_e32 v18, v18
	v_rcp_f32_e32 v19, v19
	v_mul_f32_e32 v8, v0, v22
	v_mul_f32_e32 v0, v1, v9
	v_mul_f32_e32 v9, v0, v23
	v_mul_f32_e32 v0, v2, v10
	v_mul_f32_e32 v10, v0, v24
	v_mul_f32_e32 v0, v3, v11
	v_mul_f32_e32 v4, v4, v12
	v_mul_f32_e32 v5, v5, v13
	v_mul_f32_e32 v6, v6, v14
	v_mul_f32_e32 v7, v7, v15
	v_mul_f32_e32 v3, v0, v25
	s_andn2_b64 vcc, exec, s[42:43]
	s_mov_b64 s[4:5], -1
	v_mul_f32_e32 v4, v4, v16
	v_mul_f32_e32 v5, v5, v17
	v_mul_f32_e32 v6, v6, v18
	v_mul_f32_e32 v7, v7, v19
	v_cvt_pk_bf16_f32 v0, v4, v5
	v_cvt_pk_bf16_f32 v1, v6, v7
	v_cvt_pk_bf16_f32 v2, v8, v9
	v_cvt_pk_bf16_f32 v3, v10, v3
	global_store_dwordx4 v[20:21], v[0:3], off offset:2048
	s_cbranch_vccnz .LBB0_1299
	s_branch .LBB0_1298
.LBB0_1313:
	s_waitcnt vmcnt(0)
	s_and_b64 vcc, exec, s[34:35]
	s_cbranch_vccz .Lmy_na_5
	s_barrier
.Lmy_na_5:
	v_readlane_b32 s56, v254, 58
	v_readlane_b32 s92, v254, 60
	v_readlane_b32 s14, v254, 62
	v_readlane_b32 s57, v254, 59
	v_readlane_b32 s93, v254, 61
	v_readlane_b32 s15, v254, 63
	s_barrier

; __device__ __forceinline__ unsigned cvt_pk_bf16(float lo, float hi) { unsigned r; asm volatile("v_cvt_pk_bf16_f32 %0, %1, %2" : "=v"(r) : "v"(lo), "v"(hi)); return r; }
; #define PG8_BAR __builtin_amdgcn_s_barrier()
;     __device__ __forceinline__ void half(const f32x4 (&acc)[2][4][2], int pm, int ai, int pn, int wr, int wc, int fr, int fq) const {
;         const int row0 = pm * BM + wr * 64 + fr, col0 = pn * HALF + wc * 32 + 8 * fq;
;         {
; #pragma unroll
;             for (int m = 0; m < 4; ++m) {
;                 float a[8], e[8];
; #pragma unroll
;                 for (int q = 0; q < 8; ++q) a[q] = acc[0][m][q >> 2][q & 3];
; #pragma unroll
;                 for (int q = 0; q < 8; ++q) e[q] = __builtin_amdgcn_exp2f(-a[q]);
; #pragma unroll
;                 for (int q = 0; q < 8; ++q) e[q] += 1.f;
; #pragma unroll
;                 for (int q = 0; q < 8; ++q) e[q] = __builtin_amdgcn_rcpf(e[q]);
; #pragma unroll
;                 for (int q = 0; q < 8; ++q) a[q] = a[q] * acc[1][m][q >> 2][q & 3] * e[q];
;                 u32x4 w; w.x = cvt_pk_bf16(a[0], a[1]); w.y = cvt_pk_bf16(a[2], a[3]); w.z = cvt_pk_bf16(a[4], a[5]); w.w = cvt_pk_bf16(a[6], a[7]);
;                 const int row = row0 + ai * HALF + m * 16;
;                 bf16_t* dst = O + (((size_t)(row >> 8) * (ldc >> 6) + (col0 >> 6)) * 256 + (row & 255)) * 64 + (col0 & 63);
;                 if (wt) asm volatile("global_store_dwordx4 %0, %1, off sc1\n\ts_nop 1" :: "v"(dst), "v"(w) : "memory"); else *(u32x4*)dst = w; }
; template <class Epi, class Sched, bool ALIGN_EPI = false, bool SP2 = false>
; __device__ __forceinline__ void gemm_phase(PG8_LAS unsigned char* lds, const Gemm g, const Sched& S, const Epi& E) {
;     ...
;         if constexpr (ALIGN_EPI) { if (wr == 0) PG8_BAR; }
.Lmy_peel_7_exit:
.LBB0_1660:
	v_exp_f32_e64 v159, -v120
	v_exp_f32_e64 v160, -v121
	v_exp_f32_e64 v155, -v124
	v_exp_f32_e64 v156, -v125
	v_exp_f32_e64 v157, -v126
	v_exp_f32_e64 v161, -v122
	v_exp_f32_e64 v158, -v127
	v_exp_f32_e64 v162, -v123
	s_lshl_b32 s4, s62, 8
	v_add_f32_e32 v159, 1.0, v159
	s_lshl_b32 s5, s60, 7
	s_add_i32 s12, s4, s42
	v_add_f32_e32 v160, 1.0, v160
	v_rcp_f32_e32 v159, v159
	s_or_b32 s5, s5, s43
	s_ashr_i32 s12, s12, 8
	v_add_f32_e32 v155, 1.0, v155
	v_add_f32_e32 v156, 1.0, v156
	v_add_f32_e32 v157, 1.0, v157
	v_add_f32_e32 v161, 1.0, v161
	v_rcp_f32_e32 v160, v160
	s_ashr_i32 s50, s5, 6
	v_add_f32_e32 v158, 1.0, v158
	v_add_f32_e32 v162, 1.0, v162
	v_rcp_f32_e32 v155, v155
	v_rcp_f32_e32 v156, v156
	v_rcp_f32_e32 v157, v157
	v_rcp_f32_e32 v161, v161
	s_mulk_i32 s12, 0x58
	s_ashr_i32 s51, s50, 31
	v_rcp_f32_e32 v158, v158
	v_rcp_f32_e32 v162, v162
	v_mul_f32_e32 v112, v112, v120
	s_ashr_i32 s5, s12, 31
	v_mul_f32_e32 v120, v112, v159
	v_mul_f32_e32 v112, v113, v121
	s_add_u32 s12, s12, s50
	v_mul_f32_e32 v116, v116, v124
	v_mul_f32_e32 v117, v117, v125
	v_mul_f32_e32 v118, v118, v126
	v_mul_f32_e32 v121, v112, v160
	v_mul_f32_e32 v112, v114, v122
	s_addc_u32 s13, s5, s51
	v_mul_f32_e32 v116, v116, v155
	v_mul_f32_e32 v117, v117, v156
	v_mul_f32_e32 v118, v118, v157
	v_mul_f32_e32 v119, v119, v127
	v_mul_f32_e32 v122, v112, v161
	v_mul_f32_e32 v112, v115, v123
	s_lshl_b64 s[12:13], s[12:13], 15
	v_mul_f32_e32 v119, v119, v158
	v_mul_f32_e32 v115, v112, v162
	v_cvt_pk_bf16_f32 v112, v116, v117
	v_cvt_pk_bf16_f32 v113, v118, v119
	v_lshl_add_u64 v[116:117], v[138:139], 0, s[12:13]
	v_exp_f32_e64 v118, -v104
	v_lshl_add_u64 v[116:117], v[116:117], 0, v[136:137]
	v_exp_f32_e64 v119, -v105
	v_cvt_pk_bf16_f32 v114, v120, v121
	v_cvt_pk_bf16_f32 v115, v122, v115
	global_store_dwordx4 v[116:117], v[112:115], off
	v_exp_f32_e64 v120, -v106
	v_exp_f32_e64 v121, -v107
	v_exp_f32_e64 v112, -v108
	v_exp_f32_e64 v113, -v109
	v_exp_f32_e64 v114, -v110
	v_exp_f32_e64 v115, -v111
	v_add_f32_e32 v118, 1.0, v118
	v_add_f32_e32 v119, 1.0, v119
	v_rcp_f32_e32 v118, v118
	v_add_f32_e32 v112, 1.0, v112
	v_add_f32_e32 v120, 1.0, v120
	v_rcp_f32_e32 v119, v119
	v_add_f32_e32 v113, 1.0, v113
	v_add_f32_e32 v121, 1.0, v121
	v_rcp_f32_e32 v112, v112
	v_rcp_f32_e32 v120, v120
	v_add_f32_e32 v114, 1.0, v114
	v_add_f32_e32 v115, 1.0, v115
	v_rcp_f32_e32 v113, v113
	v_rcp_f32_e32 v121, v121
	v_mul_f32_e32 v96, v96, v104
	v_rcp_f32_e32 v114, v114
	v_rcp_f32_e32 v115, v115
	v_mul_f32_e32 v104, v96, v118
	v_mul_f32_e32 v96, v97, v105
	v_mul_f32_e32 v100, v100, v108
	v_mul_f32_e32 v105, v96, v119
	v_mul_f32_e32 v96, v98, v106
	v_mul_f32_e32 v100, v100, v112
	v_mul_f32_e32 v101, v101, v109
	v_mul_f32_e32 v106, v96, v120
	v_mul_f32_e32 v96, v99, v107
	v_mul_f32_e32 v101, v101, v113
	v_mul_f32_e32 v102, v102, v110
	v_mul_f32_e32 v103, v103, v111
	v_mul_f32_e32 v99, v96, v121
	v_cvt_pk_bf16_f32 v96, v100, v101
	v_exp_f32_e64 v100, -v88
	v_mul_f32_e32 v102, v102, v114
	v_mul_f32_e32 v103, v103, v115
	v_cvt_pk_bf16_f32 v97, v102, v103
	v_cvt_pk_bf16_f32 v98, v104, v105
	v_exp_f32_e64 v101, -v89
	v_cvt_pk_bf16_f32 v99, v106, v99
	global_store_dwordx4 v[116:117], v[96:99], off offset:2048
	v_exp_f32_e64 v102, -v90
	v_exp_f32_e64 v103, -v91
	v_exp_f32_e64 v96, -v92
	v_exp_f32_e64 v98, -v94
	v_exp_f32_e64 v97, -v93
	v_exp_f32_e64 v99, -v95
	v_add_f32_e32 v100, 1.0, v100
	v_add_f32_e32 v101, 1.0, v101
	v_rcp_f32_e32 v100, v100
	v_add_f32_e32 v96, 1.0, v96
	v_add_f32_e32 v98, 1.0, v98
	v_add_f32_e32 v102, 1.0, v102
	v_rcp_f32_e32 v101, v101
	v_add_f32_e32 v97, 1.0, v97
	v_add_f32_e32 v99, 1.0, v99
	v_add_f32_e32 v103, 1.0, v103
	v_rcp_f32_e32 v96, v96
	v_rcp_f32_e32 v98, v98
	v_rcp_f32_e32 v102, v102
	v_rcp_f32_e32 v97, v97
	v_rcp_f32_e32 v99, v99
	v_rcp_f32_e32 v103, v103
	v_mul_f32_e32 v80, v80, v88
	v_mul_f32_e32 v88, v80, v100
	v_mul_f32_e32 v80, v81, v89
	v_mul_f32_e32 v84, v84, v92
	v_mul_f32_e32 v86, v86, v94
	v_mul_f32_e32 v89, v80, v101
	v_mul_f32_e32 v80, v82, v90
	v_mul_f32_e32 v84, v84, v96
	v_mul_f32_e32 v85, v85, v93
	v_mul_f32_e32 v86, v86, v98
	v_mul_f32_e32 v87, v87, v95
	v_mul_f32_e32 v90, v80, v102
	v_mul_f32_e32 v80, v83, v91
	v_mul_f32_e32 v85, v85, v97
	v_mul_f32_e32 v87, v87, v99
	v_mul_f32_e32 v83, v80, v103
	v_cvt_pk_bf16_f32 v80, v84, v85
	v_cvt_pk_bf16_f32 v81, v86, v87
	v_add_co_u32_e32 v84, vcc, s61, v116
	v_exp_f32_e64 v86, -v72
	s_nop 0
	v_addc_co_u32_e32 v85, vcc, 0, v117, vcc
	v_exp_f32_e64 v87, -v73
	v_cvt_pk_bf16_f32 v82, v88, v89
	v_cvt_pk_bf16_f32 v83, v90, v83
	global_store_dwordx4 v[84:85], v[80:83], off
	v_exp_f32_e64 v88, -v74
	v_exp_f32_e64 v89, -v75
	v_exp_f32_e64 v81, -v77
	v_exp_f32_e64 v80, -v76
	v_exp_f32_e64 v82, -v78
	v_exp_f32_e64 v83, -v79
	v_add_f32_e32 v86, 1.0, v86
	v_add_f32_e32 v87, 1.0, v87
	v_rcp_f32_e32 v86, v86
	v_add_f32_e32 v81, 1.0, v81
	v_add_f32_e32 v88, 1.0, v88
	v_rcp_f32_e32 v87, v87
	v_add_f32_e32 v80, 1.0, v80
	v_add_f32_e32 v82, 1.0, v82
	v_add_f32_e32 v89, 1.0, v89
	v_rcp_f32_e32 v81, v81
	v_rcp_f32_e32 v88, v88
	v_add_f32_e32 v83, 1.0, v83
	v_rcp_f32_e32 v80, v80
	v_rcp_f32_e32 v82, v82
	v_rcp_f32_e32 v89, v89
	v_mul_f32_e32 v64, v64, v72
	v_rcp_f32_e32 v83, v83
	v_mul_f32_e32 v72, v64, v86
	v_mul_f32_e32 v64, v65, v73
	v_mul_f32_e32 v69, v69, v77
	v_mul_f32_e32 v73, v64, v87
	v_mul_f32_e32 v64, v66, v74
	v_mul_f32_e32 v68, v68, v76
	v_mul_f32_e32 v69, v69, v81
	v_mul_f32_e32 v70, v70, v78
	v_mul_f32_e32 v74, v64, v88
	v_mul_f32_e32 v64, v67, v75
	v_mul_f32_e32 v68, v68, v80
	v_mul_f32_e32 v70, v70, v82
	v_mul_f32_e32 v71, v71, v79
	v_mul_f32_e32 v67, v64, v89
	v_cvt_pk_bf16_f32 v64, v68, v69
; __device__ __forceinline__ unsigned cvt_pk_bf16(float lo, float hi) { unsigned r; asm volatile("v_cvt_pk_bf16_f32 %0, %1, %2" : "=v"(r) : "v"(lo), "v"(hi)); return r; }
; #define PG8_BAR __builtin_amdgcn_s_barrier()
;     __device__ __forceinline__ void half(const f32x4 (&acc)[2][4][2], int pm, int ai, int pn, int wr, int wc, int fr, int fq) const {
;     ...
;             for (int m = 0; m < 4; ++m) {
;                 float a[8], e[8];
; #pragma unroll
;                 for (int q = 0; q < 8; ++q) a[q] = acc[0][m][q >> 2][q & 3];
; #pragma unroll
;                 for (int q = 0; q < 8; ++q) e[q] = __builtin_amdgcn_exp2f(-a[q]);
; #pragma unroll
;                 for (int q = 0; q < 8; ++q) e[q] += 1.f;
; #pragma unroll
;                 for (int q = 0; q < 8; ++q) e[q] = __builtin_amdgcn_rcpf(e[q]);
; #pragma unroll
;                 for (int q = 0; q < 8; ++q) a[q] = a[q] * acc[1][m][q >> 2][q & 3] * e[q];
;                 u32x4 w; w.x = cvt_pk_bf16(a[0], a[1]); w.y = cvt_pk_bf16(a[2], a[3]); w.z = cvt_pk_bf16(a[4], a[5]); w.w = cvt_pk_bf16(a[6], a[7]);
;                 const int row = row0 + ai * HALF + m * 16;
;                 bf16_t* dst = O + (((size_t)(row >> 8) * (ldc >> 6) + (col0 >> 6)) * 256 + (row & 255)) * 64 + (col0 & 63);
;                 if (wt) asm volatile("global_store_dwordx4 %0, %1, off sc1\n\ts_nop 1" :: "v"(dst), "v"(w) : "memory"); else *(u32x4*)dst = w; }
; template <class Epi, class Sched, bool ALIGN_EPI = false, bool SP2 = false>
; __device__ __forceinline__ void gemm_phase(PG8_LAS unsigned char* lds, const Gemm g, const Sched& S, const Epi& E) {
;     ...
;         if constexpr (ALIGN_EPI) { if (wr == 1) PG8_BAR; }
	v_exp_f32_e64 v69, -v56
	v_mul_f32_e32 v71, v71, v83
	v_cvt_pk_bf16_f32 v65, v70, v71
	v_exp_f32_e64 v70, -v57
	v_cvt_pk_bf16_f32 v66, v72, v73
	v_cvt_pk_bf16_f32 v67, v74, v67
	global_store_dwordx4 v[84:85], v[64:67], off offset:2048
	v_exp_f32_e64 v71, -v58
	v_exp_f32_e64 v72, -v59
	v_exp_f32_e64 v65, -v60
	v_exp_f32_e64 v66, -v61
	v_add_f32_e32 v69, 1.0, v69
	v_add_f32_e32 v70, 1.0, v70
	v_rcp_f32_e32 v69, v69
	v_exp_f32_e64 v67, -v62
	v_add_f32_e32 v65, 1.0, v65
	v_add_f32_e32 v71, 1.0, v71
	v_rcp_f32_e32 v70, v70
	v_exp_f32_e64 v68, -v63
	v_add_f32_e32 v66, 1.0, v66
	v_add_f32_e32 v72, 1.0, v72
	v_rcp_f32_e32 v65, v65
	v_rcp_f32_e32 v71, v71
	v_rcp_f32_e32 v66, v66
	v_rcp_f32_e32 v72, v72
	v_mul_f32_e32 v48, v48, v56
	v_mul_f32_e32 v56, v48, v69
	v_mul_f32_e32 v48, v49, v57
	v_add_u32_e32 v64, s4, v151
	v_add_f32_e32 v67, 1.0, v67
	v_mul_f32_e32 v52, v52, v60
	v_mul_f32_e32 v57, v48, v70
	v_mul_f32_e32 v48, v50, v58
	v_lshrrev_b32_e32 v64, 8, v64
	v_add_f32_e32 v68, 1.0, v68
	v_rcp_f32_e32 v67, v67
	v_mul_f32_e32 v52, v52, v65
	v_mul_f32_e32 v53, v53, v61
	v_mul_f32_e32 v58, v48, v71
	v_mul_f32_e32 v48, v51, v59
	v_rcp_f32_e32 v68, v68
	v_mul_f32_e32 v53, v53, v66
	v_mul_f32_e32 v51, v48, v72
	v_cvt_pk_bf16_f32 v48, v52, v53
	v_mul_i32_i24_e32 v52, 0x58, v64
	v_ashrrev_i32_e32 v53, 31, v52
	v_mul_f32_e32 v54, v54, v62
	v_lshl_add_u64 v[52:53], v[52:53], 0, s[50:51]
	v_mul_f32_e32 v54, v54, v67
	v_mul_f32_e32 v55, v55, v63
	v_lshlrev_b64 v[52:53], 15, v[52:53]
	v_mul_f32_e32 v55, v55, v68
	v_cvt_pk_bf16_f32 v49, v54, v55
	v_lshl_add_u64 v[52:53], v[140:141], 0, v[52:53]
	v_exp_f32_e64 v54, -v40
	v_lshl_add_u64 v[52:53], v[52:53], 0, v[136:137]
	v_exp_f32_e64 v55, -v41
	v_cvt_pk_bf16_f32 v50, v56, v57
	v_cvt_pk_bf16_f32 v51, v58, v51
	global_store_dwordx4 v[52:53], v[48:51], off
	v_exp_f32_e64 v56, -v42
	v_exp_f32_e64 v57, -v43
	v_exp_f32_e64 v48, -v44
	v_exp_f32_e64 v49, -v45
	v_exp_f32_e64 v50, -v46
	v_exp_f32_e64 v51, -v47
	v_add_f32_e32 v54, 1.0, v54
	v_add_f32_e32 v55, 1.0, v55
	v_rcp_f32_e32 v54, v54
	v_add_f32_e32 v48, 1.0, v48
	v_add_f32_e32 v56, 1.0, v56
	v_rcp_f32_e32 v55, v55
	v_add_f32_e32 v49, 1.0, v49
	v_add_f32_e32 v57, 1.0, v57
	v_rcp_f32_e32 v48, v48
	v_rcp_f32_e32 v56, v56
	v_add_f32_e32 v50, 1.0, v50
	v_add_f32_e32 v51, 1.0, v51
	v_rcp_f32_e32 v49, v49
	v_rcp_f32_e32 v57, v57
	v_mul_f32_e32 v32, v32, v40
	v_rcp_f32_e32 v50, v50
	v_rcp_f32_e32 v51, v51
	v_mul_f32_e32 v40, v32, v54
	v_mul_f32_e32 v32, v33, v41
	v_mul_f32_e32 v36, v36, v44
	v_mul_f32_e32 v41, v32, v55
	v_mul_f32_e32 v32, v34, v42
	v_mul_f32_e32 v36, v36, v48
	v_mul_f32_e32 v37, v37, v45
	v_mul_f32_e32 v42, v32, v56
	v_mul_f32_e32 v32, v35, v43
	v_mul_f32_e32 v37, v37, v49
	v_mul_f32_e32 v38, v38, v46
	v_mul_f32_e32 v39, v39, v47
	v_mul_f32_e32 v35, v32, v57
	v_cvt_pk_bf16_f32 v32, v36, v37
	v_exp_f32_e64 v36, -v24
	v_mul_f32_e32 v38, v38, v50
	v_mul_f32_e32 v39, v39, v51
	v_cvt_pk_bf16_f32 v33, v38, v39
	v_cvt_pk_bf16_f32 v34, v40, v41
	v_exp_f32_e64 v37, -v25
	v_cvt_pk_bf16_f32 v35, v42, v35
	global_store_dwordx4 v[52:53], v[32:35], off offset:2048
	v_exp_f32_e64 v38, -v26
	v_exp_f32_e64 v39, -v27
	v_exp_f32_e64 v34, -v30
	v_exp_f32_e64 v32, -v28
	v_exp_f32_e64 v33, -v29
	v_exp_f32_e64 v35, -v31
	v_add_f32_e32 v36, 1.0, v36
	v_add_f32_e32 v37, 1.0, v37
	v_rcp_f32_e32 v36, v36
	v_add_f32_e32 v34, 1.0, v34
	v_add_f32_e32 v38, 1.0, v38
	v_rcp_f32_e32 v37, v37
	v_add_f32_e32 v32, 1.0, v32
	v_add_f32_e32 v33, 1.0, v33
	v_add_f32_e32 v35, 1.0, v35
	v_add_f32_e32 v39, 1.0, v39
	v_rcp_f32_e32 v34, v34
	v_rcp_f32_e32 v38, v38
	v_rcp_f32_e32 v32, v32
	v_rcp_f32_e32 v33, v33
	v_rcp_f32_e32 v35, v35
	v_rcp_f32_e32 v39, v39
	v_mul_f32_e32 v16, v16, v24
	v_mul_f32_e32 v24, v16, v36
	v_mul_f32_e32 v16, v17, v25
	v_mul_f32_e32 v22, v22, v30
	v_mul_f32_e32 v25, v16, v37
	v_mul_f32_e32 v16, v18, v26
	v_mul_f32_e32 v20, v20, v28
	v_mul_f32_e32 v21, v21, v29
	v_mul_f32_e32 v22, v22, v34
	v_mul_f32_e32 v23, v23, v31
	v_mul_f32_e32 v26, v16, v38
	v_mul_f32_e32 v16, v19, v27
	v_mul_f32_e32 v20, v20, v32
	v_mul_f32_e32 v21, v21, v33
	v_mul_f32_e32 v23, v23, v35
	v_mul_f32_e32 v19, v16, v39
	v_cvt_pk_bf16_f32 v16, v20, v21
	v_cvt_pk_bf16_f32 v17, v22, v23
	v_exp_f32_e64 v22, -v8
	v_exp_f32_e64 v23, -v9
	v_cvt_pk_bf16_f32 v18, v24, v25
	v_add_co_u32_e32 v20, vcc, s61, v52
	v_exp_f32_e64 v24, -v10
	v_cvt_pk_bf16_f32 v19, v26, v19
	s_nop 0
	v_addc_co_u32_e32 v21, vcc, 0, v53, vcc
	v_exp_f32_e64 v25, -v11
	global_store_dwordx4 v[20:21], v[16:19], off
	v_add_f32_e32 v22, 1.0, v22
	v_add_f32_e32 v23, 1.0, v23
	v_exp_f32_e64 v16, -v12
	v_exp_f32_e64 v17, -v13
	v_exp_f32_e64 v18, -v14
	v_exp_f32_e64 v19, -v15
	v_rcp_f32_e32 v22, v22
	v_add_f32_e32 v24, 1.0, v24
	v_rcp_f32_e32 v23, v23
	v_add_f32_e32 v25, 1.0, v25
	v_rcp_f32_e32 v24, v24
	v_add_f32_e32 v16, 1.0, v16
	v_add_f32_e32 v17, 1.0, v17
	v_add_f32_e32 v18, 1.0, v18
	v_add_f32_e32 v19, 1.0, v19
	v_rcp_f32_e32 v25, v25
	v_mul_f32_e32 v0, v0, v8
	v_rcp_f32_e32 v16, v16
	v_rcp_f32_e32 v17, v17
	v_rcp_f32_e32 v18, v18
	v_rcp_f32_e32 v19, v19
	v_mul_f32_e32 v8, v0, v22
	v_mul_f32_e32 v0, v1, v9
	v_mul_f32_e32 v9, v0, v23
	v_mul_f32_e32 v0, v2, v10
	v_mul_f32_e32 v10, v0, v24
	v_mul_f32_e32 v0, v3, v11
	v_mul_f32_e32 v4, v4, v12
	v_mul_f32_e32 v5, v5, v13
	v_mul_f32_e32 v6, v6, v14
	v_mul_f32_e32 v7, v7, v15
	v_mul_f32_e32 v3, v0, v25
	s_andn2_b64 vcc, exec, s[44:45]
	s_mov_b64 s[4:5], -1
	v_mul_f32_e32 v4, v4, v16
	v_mul_f32_e32 v5, v5, v17
	v_mul_f32_e32 v6, v6, v18
	v_mul_f32_e32 v7, v7, v19
	v_cvt_pk_bf16_f32 v0, v4, v5
	v_cvt_pk_bf16_f32 v1, v6, v7
	v_cvt_pk_bf16_f32 v2, v8, v9
	v_cvt_pk_bf16_f32 v3, v10, v3
	global_store_dwordx4 v[20:21], v[0:3], off offset:2048
	s_cbranch_vccnz .LBB0_1649
	s_branch .LBB0_1648

; __device__ __forceinline__ unsigned cvt_pk_bf16(float lo, float hi) { unsigned r; asm volatile("v_cvt_pk_bf16_f32 %0, %1, %2" : "=v"(r) : "v"(lo), "v"(hi)); return r; }
; #define PG8_BAR __builtin_amdgcn_s_barrier()
;     __device__ __forceinline__ void half(const f32x4 (&acc)[2][4][2], int pm, int ai, int pn, int wr, int wc, int fr, int fq) const {
;         const int row0 = pm * BM + wr * 64 + fr, col0 = pn * HALF + wc * 32 + 8 * fq;
;         {
; #pragma unroll
;             for (int m = 0; m < 4; ++m) {
;                 float a[8], e[8];
; #pragma unroll
;                 for (int q = 0; q < 8; ++q) a[q] = acc[0][m][q >> 2][q & 3];
; #pragma unroll
;                 for (int q = 0; q < 8; ++q) e[q] = __builtin_amdgcn_exp2f(-a[q]);
; #pragma unroll
;                 for (int q = 0; q < 8; ++q) e[q] += 1.f;
; #pragma unroll
;                 for (int q = 0; q < 8; ++q) e[q] = __builtin_amdgcn_rcpf(e[q]);
; #pragma unroll
;                 for (int q = 0; q < 8; ++q) a[q] = a[q] * acc[1][m][q >> 2][q & 3] * e[q];
;                 u32x4 w; w.x = cvt_pk_bf16(a[0], a[1]); w.y = cvt_pk_bf16(a[2], a[3]); w.z = cvt_pk_bf16(a[4], a[5]); w.w = cvt_pk_bf16(a[6], a[7]);
;                 const int row = row0 + ai * HALF + m * 16;
;                 bf16_t* dst = O + (((size_t)(row >> 8) * (ldc >> 6) + (col0 >> 6)) * 256 + (row & 255)) * 64 + (col0 & 63);
;                 if (wt) asm volatile("global_store_dwordx4 %0, %1, off sc1\n\ts_nop 1" :: "v"(dst), "v"(w) : "memory"); else *(u32x4*)dst = w; }
; template <class Epi, class Sched, bool ALIGN_EPI = false, bool SP2 = false>
; __device__ __forceinline__ void gemm_phase(PG8_LAS unsigned char* lds, const Gemm g, const Sched& S, const Epi& E) {
;     ...
;         if constexpr (ALIGN_EPI) { if (wr == 0) PG8_BAR; }
.Lmy_peel_11_exit:
.LBB0_3061:
	v_exp_f32_e64 v159, -v120
	v_exp_f32_e64 v160, -v121
	v_exp_f32_e64 v155, -v124
	v_exp_f32_e64 v156, -v125
	v_exp_f32_e64 v157, -v126
	v_exp_f32_e64 v161, -v122
	v_exp_f32_e64 v158, -v127
	v_exp_f32_e64 v162, -v123
	s_lshl_b32 s4, s38, 8
	v_add_f32_e32 v159, 1.0, v159
	s_lshl_b32 s5, s34, 7
	s_add_i32 s12, s4, s46
	v_add_f32_e32 v160, 1.0, v160
	v_rcp_f32_e32 v159, v159
	s_or_b32 s5, s5, s47
	s_ashr_i32 s12, s12, 8
	v_add_f32_e32 v155, 1.0, v155
	v_add_f32_e32 v156, 1.0, v156
	v_add_f32_e32 v157, 1.0, v157
	v_add_f32_e32 v161, 1.0, v161
	v_rcp_f32_e32 v160, v160
	s_ashr_i32 s34, s5, 6
	v_add_f32_e32 v158, 1.0, v158
	v_add_f32_e32 v162, 1.0, v162
	v_rcp_f32_e32 v155, v155
	v_rcp_f32_e32 v156, v156
	v_rcp_f32_e32 v157, v157
	v_rcp_f32_e32 v161, v161
	s_mulk_i32 s12, 0x58
	s_ashr_i32 s35, s34, 31
	v_rcp_f32_e32 v158, v158
	v_rcp_f32_e32 v162, v162
	v_mul_f32_e32 v112, v112, v120
	s_ashr_i32 s5, s12, 31
	v_mul_f32_e32 v120, v112, v159
	v_mul_f32_e32 v112, v113, v121
	s_add_u32 s12, s12, s34
	v_mul_f32_e32 v116, v116, v124
	v_mul_f32_e32 v117, v117, v125
	v_mul_f32_e32 v118, v118, v126
	v_mul_f32_e32 v121, v112, v160
	v_mul_f32_e32 v112, v114, v122
	s_addc_u32 s13, s5, s35
	v_mul_f32_e32 v116, v116, v155
	v_mul_f32_e32 v117, v117, v156
	v_mul_f32_e32 v118, v118, v157
	v_mul_f32_e32 v119, v119, v127
	v_mul_f32_e32 v122, v112, v161
	v_mul_f32_e32 v112, v115, v123
	s_lshl_b64 s[12:13], s[12:13], 15
	v_mul_f32_e32 v119, v119, v158
	v_mul_f32_e32 v115, v112, v162
	v_cvt_pk_bf16_f32 v112, v116, v117
	v_cvt_pk_bf16_f32 v113, v118, v119
	v_lshl_add_u64 v[116:117], v[138:139], 0, s[12:13]
	v_exp_f32_e64 v118, -v104
	v_lshl_add_u64 v[116:117], v[116:117], 0, v[136:137]
	v_exp_f32_e64 v119, -v105
	v_cvt_pk_bf16_f32 v114, v120, v121
	v_cvt_pk_bf16_f32 v115, v122, v115
	global_store_dwordx4 v[116:117], v[112:115], off
	v_exp_f32_e64 v120, -v106
	v_exp_f32_e64 v121, -v107
	v_exp_f32_e64 v112, -v108
	v_exp_f32_e64 v113, -v109
	v_exp_f32_e64 v114, -v110
	v_exp_f32_e64 v115, -v111
	v_add_f32_e32 v118, 1.0, v118
	v_add_f32_e32 v119, 1.0, v119
	v_rcp_f32_e32 v118, v118
	v_add_f32_e32 v112, 1.0, v112
	v_add_f32_e32 v120, 1.0, v120
	v_rcp_f32_e32 v119, v119
	v_add_f32_e32 v113, 1.0, v113
	v_add_f32_e32 v121, 1.0, v121
	v_rcp_f32_e32 v112, v112
	v_rcp_f32_e32 v120, v120
	v_add_f32_e32 v114, 1.0, v114
	v_add_f32_e32 v115, 1.0, v115
	v_rcp_f32_e32 v113, v113
	v_rcp_f32_e32 v121, v121
	v_mul_f32_e32 v96, v96, v104
	v_rcp_f32_e32 v114, v114
	v_rcp_f32_e32 v115, v115
	v_mul_f32_e32 v104, v96, v118
	v_mul_f32_e32 v96, v97, v105
	v_mul_f32_e32 v100, v100, v108
	v_mul_f32_e32 v105, v96, v119
	v_mul_f32_e32 v96, v98, v106
	v_mul_f32_e32 v100, v100, v112
	v_mul_f32_e32 v101, v101, v109
	v_mul_f32_e32 v106, v96, v120
	v_mul_f32_e32 v96, v99, v107
	v_mul_f32_e32 v101, v101, v113
	v_mul_f32_e32 v102, v102, v110
	v_mul_f32_e32 v103, v103, v111
	v_mul_f32_e32 v99, v96, v121
	v_cvt_pk_bf16_f32 v96, v100, v101
	v_exp_f32_e64 v100, -v88
	v_mul_f32_e32 v102, v102, v114
	v_mul_f32_e32 v103, v103, v115
	v_cvt_pk_bf16_f32 v97, v102, v103
	v_cvt_pk_bf16_f32 v98, v104, v105
	v_exp_f32_e64 v101, -v89
	v_cvt_pk_bf16_f32 v99, v106, v99
	global_store_dwordx4 v[116:117], v[96:99], off offset:2048
	v_exp_f32_e64 v102, -v90
	v_exp_f32_e64 v103, -v91
	v_exp_f32_e64 v96, -v92
	v_exp_f32_e64 v98, -v94
	v_exp_f32_e64 v97, -v93
	v_exp_f32_e64 v99, -v95
	v_add_f32_e32 v100, 1.0, v100
	v_add_f32_e32 v101, 1.0, v101
	v_rcp_f32_e32 v100, v100
	v_add_f32_e32 v96, 1.0, v96
	v_add_f32_e32 v98, 1.0, v98
	v_add_f32_e32 v102, 1.0, v102
	v_rcp_f32_e32 v101, v101
	v_add_f32_e32 v97, 1.0, v97
	v_add_f32_e32 v99, 1.0, v99
	v_add_f32_e32 v103, 1.0, v103
	v_rcp_f32_e32 v96, v96
	v_rcp_f32_e32 v98, v98
	v_rcp_f32_e32 v102, v102
	v_rcp_f32_e32 v97, v97
	v_rcp_f32_e32 v99, v99
	v_rcp_f32_e32 v103, v103
	v_mul_f32_e32 v80, v80, v88
	v_mul_f32_e32 v88, v80, v100
	v_mul_f32_e32 v80, v81, v89
	v_mul_f32_e32 v84, v84, v92
	v_mul_f32_e32 v86, v86, v94
	v_mul_f32_e32 v89, v80, v101
	v_mul_f32_e32 v80, v82, v90
	v_mul_f32_e32 v84, v84, v96
	v_mul_f32_e32 v85, v85, v93
	v_mul_f32_e32 v86, v86, v98
	v_mul_f32_e32 v87, v87, v95
	v_mul_f32_e32 v90, v80, v102
	v_mul_f32_e32 v80, v83, v91
	v_mul_f32_e32 v85, v85, v97
	v_mul_f32_e32 v87, v87, v99
	v_mul_f32_e32 v83, v80, v103
	v_cvt_pk_bf16_f32 v80, v84, v85
	v_cvt_pk_bf16_f32 v81, v86, v87
	v_add_co_u32_e32 v84, vcc, s52, v116
	v_exp_f32_e64 v86, -v72
	s_nop 0
	v_addc_co_u32_e32 v85, vcc, 0, v117, vcc
	v_exp_f32_e64 v87, -v73
	v_cvt_pk_bf16_f32 v82, v88, v89
	v_cvt_pk_bf16_f32 v83, v90, v83
	global_store_dwordx4 v[84:85], v[80:83], off
	v_exp_f32_e64 v88, -v74
	v_exp_f32_e64 v89, -v75
	v_exp_f32_e64 v81, -v77
	v_exp_f32_e64 v80, -v76
	v_exp_f32_e64 v82, -v78
	v_exp_f32_e64 v83, -v79
	v_add_f32_e32 v86, 1.0, v86
	v_add_f32_e32 v87, 1.0, v87
	v_rcp_f32_e32 v86, v86
	v_add_f32_e32 v81, 1.0, v81
	v_add_f32_e32 v88, 1.0, v88
	v_rcp_f32_e32 v87, v87
	v_add_f32_e32 v80, 1.0, v80
	v_add_f32_e32 v82, 1.0, v82
	v_add_f32_e32 v89, 1.0, v89
	v_rcp_f32_e32 v81, v81
	v_rcp_f32_e32 v88, v88
	v_add_f32_e32 v83, 1.0, v83
	v_rcp_f32_e32 v80, v80
	v_rcp_f32_e32 v82, v82
	v_rcp_f32_e32 v89, v89
	v_mul_f32_e32 v64, v64, v72
	v_rcp_f32_e32 v83, v83
	v_mul_f32_e32 v72, v64, v86
	v_mul_f32_e32 v64, v65, v73
	v_mul_f32_e32 v69, v69, v77
	v_mul_f32_e32 v73, v64, v87
	v_mul_f32_e32 v64, v66, v74
	v_mul_f32_e32 v68, v68, v76
	v_mul_f32_e32 v69, v69, v81
	v_mul_f32_e32 v70, v70, v78
	v_mul_f32_e32 v74, v64, v88
	v_mul_f32_e32 v64, v67, v75
	v_mul_f32_e32 v68, v68, v80
	v_mul_f32_e32 v70, v70, v82
	v_mul_f32_e32 v71, v71, v79
	v_mul_f32_e32 v67, v64, v89
	v_cvt_pk_bf16_f32 v64, v68, v69
; __device__ __forceinline__ unsigned cvt_pk_bf16(float lo, float hi) { unsigned r; asm volatile("v_cvt_pk_bf16_f32 %0, %1, %2" : "=v"(r) : "v"(lo), "v"(hi)); return r; }
; __device__ __forceinline__ unsigned xb_add(unsigned* p, unsigned v) { return __hip_atomic_fetch_add(p, v, __ATOMIC_RELAXED, __HIP_MEMORY_SCOPE_AGENT); }
;     __device__ __forceinline__ void half(const f32x4 (&acc)[2][4][2], int pm, int ai, int pn, int wr, int wc, int fr, int fq) const {
;     ...
;             for (int m = 0; m < 4; ++m) {
;                 float a[8], e[8];
; #pragma unroll
;                 for (int q = 0; q < 8; ++q) a[q] = acc[0][m][q >> 2][q & 3];
; #pragma unroll
;                 for (int q = 0; q < 8; ++q) e[q] = __builtin_amdgcn_exp2f(-a[q]);
; #pragma unroll
;                 for (int q = 0; q < 8; ++q) e[q] += 1.f;
; #pragma unroll
;                 for (int q = 0; q < 8; ++q) e[q] = __builtin_amdgcn_rcpf(e[q]);
; #pragma unroll
;                 for (int q = 0; q < 8; ++q) a[q] = a[q] * acc[1][m][q >> 2][q & 3] * e[q];
;                 u32x4 w; w.x = cvt_pk_bf16(a[0], a[1]); w.y = cvt_pk_bf16(a[2], a[3]); w.z = cvt_pk_bf16(a[4], a[5]); w.w = cvt_pk_bf16(a[6], a[7]);
;                 const int row = row0 + ai * HALF + m * 16;
;                 bf16_t* dst = O + (((size_t)(row >> 8) * (ldc >> 6) + (col0 >> 6)) * 256 + (row & 255)) * 64 + (col0 & 63);
;                 if (wt) asm volatile("global_store_dwordx4 %0, %1, off sc1\n\ts_nop 1" :: "v"(dst), "v"(w) : "memory"); else *(u32x4*)dst = w; }
; __device__ __forceinline__ void xcd_barrier(const XcdBarrier& b) {
;     asm volatile("s_waitcnt vmcnt(0)" ::: "memory");
;     __syncthreads();
;     if (mk_tid() == 0) {
;         unsigned* bar = b.bar;
;         __builtin_amdgcn_s_waitcnt(0);
;         unsigned nloc = b.st[0], nx = b.st[1];
;         if (nloc == 0u) { xcd_barrier_complete(bar, b.x, nloc, nx); b.st[0] = nloc; b.st[1] = nx; }
;         const unsigned old = xb_add(&bar[XB_XSUB(b.x)], 1u);
	v_exp_f32_e64 v69, -v56
	v_mul_f32_e32 v71, v71, v83
	v_cvt_pk_bf16_f32 v65, v70, v71
	v_exp_f32_e64 v70, -v57
	v_cvt_pk_bf16_f32 v66, v72, v73
	v_cvt_pk_bf16_f32 v67, v74, v67
	global_store_dwordx4 v[84:85], v[64:67], off offset:2048
	v_exp_f32_e64 v71, -v58
	v_exp_f32_e64 v72, -v59
	v_exp_f32_e64 v65, -v60
	v_exp_f32_e64 v66, -v61
	v_add_f32_e32 v69, 1.0, v69
	v_add_f32_e32 v70, 1.0, v70
	v_rcp_f32_e32 v69, v69
	v_exp_f32_e64 v67, -v62
	v_add_f32_e32 v65, 1.0, v65
	v_add_f32_e32 v71, 1.0, v71
	v_rcp_f32_e32 v70, v70
	v_exp_f32_e64 v68, -v63
	v_add_f32_e32 v66, 1.0, v66
	v_add_f32_e32 v72, 1.0, v72
	v_rcp_f32_e32 v65, v65
	v_rcp_f32_e32 v71, v71
	v_rcp_f32_e32 v66, v66
	v_rcp_f32_e32 v72, v72
	v_mul_f32_e32 v48, v48, v56
	v_mul_f32_e32 v56, v48, v69
	v_mul_f32_e32 v48, v49, v57
	v_add_u32_e32 v64, s4, v151
	v_add_f32_e32 v67, 1.0, v67
	v_mul_f32_e32 v52, v52, v60
	v_mul_f32_e32 v57, v48, v70
	v_mul_f32_e32 v48, v50, v58
	v_lshrrev_b32_e32 v64, 8, v64
	v_add_f32_e32 v68, 1.0, v68
	v_rcp_f32_e32 v67, v67
	v_mul_f32_e32 v52, v52, v65
	v_mul_f32_e32 v53, v53, v61
	v_mul_f32_e32 v58, v48, v71
	v_mul_f32_e32 v48, v51, v59
	v_rcp_f32_e32 v68, v68
	v_mul_f32_e32 v53, v53, v66
	v_mul_f32_e32 v51, v48, v72
	v_cvt_pk_bf16_f32 v48, v52, v53
	v_mul_i32_i24_e32 v52, 0x58, v64
	v_ashrrev_i32_e32 v53, 31, v52
	v_mul_f32_e32 v54, v54, v62
	v_lshl_add_u64 v[52:53], v[52:53], 0, s[34:35]
	v_mul_f32_e32 v54, v54, v67
	v_mul_f32_e32 v55, v55, v63
	v_lshlrev_b64 v[52:53], 15, v[52:53]
	v_mul_f32_e32 v55, v55, v68
	v_cvt_pk_bf16_f32 v49, v54, v55
	v_lshl_add_u64 v[52:53], v[140:141], 0, v[52:53]
	v_exp_f32_e64 v54, -v40
	v_lshl_add_u64 v[52:53], v[52:53], 0, v[136:137]
	v_exp_f32_e64 v55, -v41
	v_cvt_pk_bf16_f32 v50, v56, v57
	v_cvt_pk_bf16_f32 v51, v58, v51
	global_store_dwordx4 v[52:53], v[48:51], off
	v_exp_f32_e64 v56, -v42
	v_exp_f32_e64 v57, -v43
	v_exp_f32_e64 v48, -v44
	v_exp_f32_e64 v49, -v45
	v_exp_f32_e64 v50, -v46
	v_exp_f32_e64 v51, -v47
	v_add_f32_e32 v54, 1.0, v54
	v_add_f32_e32 v55, 1.0, v55
	v_rcp_f32_e32 v54, v54
	v_add_f32_e32 v48, 1.0, v48
	v_add_f32_e32 v56, 1.0, v56
	v_rcp_f32_e32 v55, v55
	v_add_f32_e32 v49, 1.0, v49
	v_add_f32_e32 v57, 1.0, v57
	v_rcp_f32_e32 v48, v48
	v_rcp_f32_e32 v56, v56
	v_add_f32_e32 v50, 1.0, v50
	v_add_f32_e32 v51, 1.0, v51
	v_rcp_f32_e32 v49, v49
	v_rcp_f32_e32 v57, v57
	v_mul_f32_e32 v32, v32, v40
	v_rcp_f32_e32 v50, v50
	v_rcp_f32_e32 v51, v51
	v_mul_f32_e32 v40, v32, v54
	v_mul_f32_e32 v32, v33, v41
	v_mul_f32_e32 v36, v36, v44
	v_mul_f32_e32 v41, v32, v55
	v_mul_f32_e32 v32, v34, v42
	v_mul_f32_e32 v36, v36, v48
	v_mul_f32_e32 v37, v37, v45
	v_mul_f32_e32 v42, v32, v56
	v_mul_f32_e32 v32, v35, v43
	v_mul_f32_e32 v37, v37, v49
	v_mul_f32_e32 v38, v38, v46
	v_mul_f32_e32 v39, v39, v47
	v_mul_f32_e32 v35, v32, v57
	v_cvt_pk_bf16_f32 v32, v36, v37
	v_exp_f32_e64 v36, -v24
	v_mul_f32_e32 v38, v38, v50
	v_mul_f32_e32 v39, v39, v51
	v_cvt_pk_bf16_f32 v33, v38, v39
	v_cvt_pk_bf16_f32 v34, v40, v41
	v_exp_f32_e64 v37, -v25
	v_cvt_pk_bf16_f32 v35, v42, v35
	global_store_dwordx4 v[52:53], v[32:35], off offset:2048
	v_exp_f32_e64 v38, -v26
	v_exp_f32_e64 v39, -v27
	v_exp_f32_e64 v34, -v30
	v_exp_f32_e64 v32, -v28
	v_exp_f32_e64 v33, -v29
	v_exp_f32_e64 v35, -v31
	v_add_f32_e32 v36, 1.0, v36
	v_add_f32_e32 v37, 1.0, v37
	v_rcp_f32_e32 v36, v36
	v_add_f32_e32 v34, 1.0, v34
	v_add_f32_e32 v38, 1.0, v38
	v_rcp_f32_e32 v37, v37
	v_add_f32_e32 v32, 1.0, v32
	v_add_f32_e32 v33, 1.0, v33
	v_add_f32_e32 v35, 1.0, v35
	v_add_f32_e32 v39, 1.0, v39
	v_rcp_f32_e32 v34, v34
	v_rcp_f32_e32 v38, v38
	v_rcp_f32_e32 v32, v32
	v_rcp_f32_e32 v33, v33
	v_rcp_f32_e32 v35, v35
	v_rcp_f32_e32 v39, v39
	v_mul_f32_e32 v16, v16, v24
	v_mul_f32_e32 v24, v16, v36
	v_mul_f32_e32 v16, v17, v25
	v_mul_f32_e32 v22, v22, v30
	v_mul_f32_e32 v25, v16, v37
	v_mul_f32_e32 v16, v18, v26
	v_mul_f32_e32 v20, v20, v28
	v_mul_f32_e32 v21, v21, v29
	v_mul_f32_e32 v22, v22, v34
	v_mul_f32_e32 v23, v23, v31
	v_mul_f32_e32 v26, v16, v38
	v_mul_f32_e32 v16, v19, v27
	v_mul_f32_e32 v20, v20, v32
	v_mul_f32_e32 v21, v21, v33
	v_mul_f32_e32 v23, v23, v35
	v_mul_f32_e32 v19, v16, v39
	v_cvt_pk_bf16_f32 v16, v20, v21
	v_cvt_pk_bf16_f32 v17, v22, v23
	v_exp_f32_e64 v22, -v8
	v_exp_f32_e64 v23, -v9
	v_cvt_pk_bf16_f32 v18, v24, v25
	v_add_co_u32_e32 v20, vcc, s52, v52
	v_exp_f32_e64 v24, -v10
	v_cvt_pk_bf16_f32 v19, v26, v19
	s_nop 0
	v_addc_co_u32_e32 v21, vcc, 0, v53, vcc
	v_exp_f32_e64 v25, -v11
	global_store_dwordx4 v[20:21], v[16:19], off
	v_add_f32_e32 v22, 1.0, v22
	v_add_f32_e32 v23, 1.0, v23
	v_exp_f32_e64 v16, -v12
	v_exp_f32_e64 v17, -v13
	v_exp_f32_e64 v18, -v14
	v_exp_f32_e64 v19, -v15
	v_rcp_f32_e32 v22, v22
	v_add_f32_e32 v24, 1.0, v24
	v_rcp_f32_e32 v23, v23
	v_add_f32_e32 v25, 1.0, v25
	v_rcp_f32_e32 v24, v24
	v_add_f32_e32 v16, 1.0, v16
	v_add_f32_e32 v17, 1.0, v17
	v_add_f32_e32 v18, 1.0, v18
	v_add_f32_e32 v19, 1.0, v19
	v_rcp_f32_e32 v25, v25
	v_mul_f32_e32 v0, v0, v8
	v_rcp_f32_e32 v16, v16
	v_rcp_f32_e32 v17, v17
	v_rcp_f32_e32 v18, v18
	v_rcp_f32_e32 v19, v19
	v_mul_f32_e32 v8, v0, v22
	v_mul_f32_e32 v0, v1, v9
	v_mul_f32_e32 v9, v0, v23
	v_mul_f32_e32 v0, v2, v10
	v_mul_f32_e32 v10, v0, v24
	v_mul_f32_e32 v0, v3, v11
	v_mul_f32_e32 v4, v4, v12
	v_mul_f32_e32 v5, v5, v13
	v_mul_f32_e32 v6, v6, v14
	v_mul_f32_e32 v7, v7, v15
	v_mul_f32_e32 v3, v0, v25
	s_andn2_b64 vcc, exec, s[36:37]
	s_mov_b64 s[4:5], -1
	v_mul_f32_e32 v4, v4, v16
	v_mul_f32_e32 v5, v5, v17
	v_mul_f32_e32 v6, v6, v18
	v_mul_f32_e32 v7, v7, v19
	v_cvt_pk_bf16_f32 v0, v4, v5
	v_cvt_pk_bf16_f32 v1, v6, v7
	v_cvt_pk_bf16_f32 v2, v8, v9
	v_cvt_pk_bf16_f32 v3, v10, v3
	global_store_dwordx4 v[20:21], v[0:3], off offset:2048
	s_cbranch_vccnz .LBB0_3050
	s_branch .LBB0_3049
.LBB0_3064:
	s_waitcnt vmcnt(0)
	s_and_b64 vcc, exec, s[18:19]
	s_cbranch_vccz .Lmy_na_11
	s_barrier
.Lmy_na_11:
	s_barrier
.LBB0_3065:
	s_waitcnt vmcnt(0)
	s_waitcnt vmcnt(0)
	s_barrier
	s_getreg_b32 s0, hwreg(HW_REG_HW_ID, 0, 6)
	s_lshl_b32 s0, s0, 2
	s_and_b32 s0, s0, 0xfc
	s_or_b32 s0, s0, 0x27e00
	v_mov_b32_e32 v0, s0
	ds_read_b32 v0, v0
	s_waitcnt lgkmcnt(0)
	v_readfirstlane_b32 s0, v0
	v_mbcnt_lo_u32_b32 v0, -1, 0
	v_mbcnt_hi_u32_b32 v0, -1, v0
	s_lshl_b32 s0, s0, 6
	v_sub_u32_e32 v0, 0, v0
	v_cmp_eq_u32_e32 vcc, s0, v0
	s_and_saveexec_b64 s[0:1], vcc
	s_cbranch_execz .LBB0_3117
	s_add_i32 s3, 0, 0x27f20
	v_mov_b32_e32 v0, s3
	s_waitcnt vmcnt(0) expcnt(0) lgkmcnt(0)
	ds_read_b32 v2, v0
	s_add_i32 s3, 0, 0x27f24
	v_mov_b32_e32 v0, s3
	ds_read_b32 v0, v0
	s_waitcnt lgkmcnt(1)
	v_cmp_ne_u32_e32 vcc, 0, v2
	s_cbranch_vccnz .LBB0_3081
	v_readlane_b32 s6, v253, 34
	v_readlane_b32 s7, v253, 35
	s_load_dwordx2 s[4:5], s[6:7], 0x4
	s_mov_b32 s6, 1
	v_mov_b32_e32 v16, 0
	s_waitcnt lgkmcnt(0)
	s_mul_i32 s3, s4, s88
	s_mul_i32 s3, s3, s5
	s_branch .LBB0_3069
